# MFMA order m-major within each 8-MFMA k-block: A operand held for 4 MFMAs, B snaked
# baseline (speedup 1.0000x reference)
; #define PG8_STAGE(bufoff, gbase, voff) do { _Pragma("unroll") for (int _i = 0; _i < 2; ++_i) \
;         __builtin_amdgcn_global_load_lds((const unsigned*)((const char*)(gbase) + (voff)[_i]), (PG8_LAS unsigned*)(lds + (bufoff) + ldsw + _i * 8192), 16, 0, 0); } while (0)
; #define PG8_LDA(dst, b, h) do { _Pragma("unroll") for (int m = 0; m < 4; ++m) _Pragma("unroll") for (int k = 0; k < 2; ++k) dst[m][k] = *(const PG8_LAS bf16x8*)(lds + PG8_SA(b, h) + aoff + m * 2048 + k * 1024); } while (0)
; #define PG8_LDB(dst, b, h) do { _Pragma("unroll") for (int n = 0; n < 2; ++n) _Pragma("unroll") for (int k = 0; k < 2; ++k) dst[n][k] = *(const PG8_LAS bf16x8*)(lds + PG8_SB(b, h) + boff + n * 2048 + k * 1024); } while (0)
; #define PG8_MMA(ai, bj, At, Bt) do { __builtin_amdgcn_s_setprio(1); _Pragma("unroll") for (int m = 0; m < 4; ++m) _Pragma("unroll") for (int n = 0; n < 2; ++n) _Pragma("unroll") for (int k = 0; k < 2; ++k) \
;         acc[ai][bj][m][n] = __builtin_amdgcn_mfma_f32_16x16x32_bf16(Bt[n][k], At[m][k], acc[ai][bj][m][n], 0, 0, 0); __builtin_amdgcn_s_setprio(0); } while (0)
; #define PG8_WAIT_V(n) asm volatile("s_waitcnt vmcnt(" #n ")" ::: "memory")
; #define PG8_WAIT_L(n) asm volatile("s_waitcnt lgkmcnt(" #n ")" ::: "memory")
; #define PG8_BAR __builtin_amdgcn_s_barrier()
; #define PG8_SCHED __builtin_amdgcn_sched_barrier(0)
; template <class Epi, class Sched, bool ALIGN_EPI = false, bool SP2 = false>
; __device__ __forceinline__ void gemm_phase(PG8_LAS unsigned char* lds, const Gemm g, const Sched& S, const Epi& E) {
;     ...
;             PG8_LDB(B0, 0, 0); PG8_LDB(B1, 0, 1); PG8_SCHED; PG8_LDA(At, 0, 0); PG8_STAGE(PG8_SA(1, 1), a1 + hstep, voffA);
;             PG8_WAIT_V(8); PG8_WAIT_L(0); PG8_BAR; PG8_MMA(0, 0, At, B0); PG8_MMA(0, 1, At, B1); PG8_BAR; PG8_SCHED;
;             PG8_LDA(At, 0, 1); PG8_STAGE(PG8_SB(0, 0), b2, voffB); PG8_STAGE(PG8_SB(0, 1), b2 + hstepB, voffB); PG8_STAGE(PG8_SA(0, 0), a2, voffA);
;             PG8_WAIT_V(8); PG8_WAIT_L(0); PG8_BAR; PG8_MMA(1, 0, At, B0); PG8_MMA(1, 1, At, B1); PG8_BAR; PG8_SCHED;
.LBB0_402:
	ds_read_b128 v[82:85], v178
	ds_read_b128 v[86:89], v178 offset:1024
	ds_read_b128 v[90:93], v178 offset:2048
	ds_read_b128 v[94:97], v178 offset:3072
	ds_read_b128 v[186:189], v179
	ds_read_b128 v[190:193], v179 offset:1024
	ds_read_b128 v[194:197], v179 offset:2048
	ds_read_b128 v[198:201], v179 offset:3072
	s_add_u32 s10, s6, 0xfff00080
	s_addc_u32 s11, s7, -1
	s_cmp_eq_u32 s51, 60
	s_cselect_b32 s35, s23, s11
	s_cselect_b32 s34, s47, s10
	s_cselect_b32 s11, s21, s50
	s_cselect_b32 s10, s48, s49
	v_lshl_add_u64 v[234:235], s[6:7], 0, v[158:159]
	s_add_i32 m0, s29, 0xc000
	ds_read_b128 v[202:205], v180
	ds_read_b128 v[206:209], v180 offset:1024
	ds_read_b128 v[210:213], v180 offset:2048
	ds_read_b128 v[214:217], v180 offset:3072
	ds_read_b128 v[218:221], v180 offset:4096
	ds_read_b128 v[222:225], v180 offset:5120
	ds_read_b128 v[226:229], v180 offset:6144
	ds_read_b128 v[230:233], v180 offset:7168
	global_load_lds_dwordx4 v[234:235], off
	v_lshl_add_u64 v[234:235], s[6:7], 0, v[160:161]
	s_add_i32 m0, s29, 0xe000
	s_nop 0
	global_load_lds_dwordx4 v[234:235], off
	s_waitcnt vmcnt(8)
	s_waitcnt lgkmcnt(0)
	s_barrier
	s_setprio 1
	s_waitcnt lgkmcnt(0)
	v_mfma_f32_16x16x32_bf16 v[142:145], v[82:85], v[202:205], v[142:145]
	v_mfma_f32_16x16x32_bf16 v[126:129], v[82:85], v[210:213], v[126:129]
	v_mfma_f32_16x16x32_bf16 v[110:113], v[82:85], v[218:221], v[110:113]
	v_mfma_f32_16x16x32_bf16 v[78:81], v[82:85], v[226:229], v[78:81]
	v_mfma_f32_16x16x32_bf16 v[74:77], v[90:93], v[226:229], v[74:77]
	v_mfma_f32_16x16x32_bf16 v[106:109], v[90:93], v[218:221], v[106:109]
	v_mfma_f32_16x16x32_bf16 v[122:125], v[90:93], v[210:213], v[122:125]
	v_mfma_f32_16x16x32_bf16 v[138:141], v[90:93], v[202:205], v[138:141]
	v_mfma_f32_16x16x32_bf16 v[142:145], v[86:89], v[206:209], v[142:145]
	v_mfma_f32_16x16x32_bf16 v[126:129], v[86:89], v[214:217], v[126:129]
	v_mfma_f32_16x16x32_bf16 v[110:113], v[86:89], v[222:225], v[110:113]
	v_mfma_f32_16x16x32_bf16 v[78:81], v[86:89], v[230:233], v[78:81]
	v_mfma_f32_16x16x32_bf16 v[74:77], v[94:97], v[230:233], v[74:77]
	v_mfma_f32_16x16x32_bf16 v[106:109], v[94:97], v[222:225], v[106:109]
	v_mfma_f32_16x16x32_bf16 v[122:125], v[94:97], v[214:217], v[122:125]
	v_mfma_f32_16x16x32_bf16 v[138:141], v[94:97], v[206:209], v[138:141]
	s_setprio 0
	s_setprio 1
	v_mfma_f32_16x16x32_bf16 v[134:137], v[186:189], v[202:205], v[134:137]
	v_mfma_f32_16x16x32_bf16 v[118:121], v[186:189], v[210:213], v[118:121]
	v_mfma_f32_16x16x32_bf16 v[102:105], v[186:189], v[218:221], v[102:105]
	v_mfma_f32_16x16x32_bf16 v[70:73], v[186:189], v[226:229], v[70:73]
	v_mfma_f32_16x16x32_bf16 v[66:69], v[194:197], v[226:229], v[66:69]
	v_mfma_f32_16x16x32_bf16 v[98:101], v[194:197], v[218:221], v[98:101]
	v_mfma_f32_16x16x32_bf16 v[114:117], v[194:197], v[210:213], v[114:117]
	v_mfma_f32_16x16x32_bf16 v[130:133], v[194:197], v[202:205], v[130:133]
	v_mfma_f32_16x16x32_bf16 v[134:137], v[190:193], v[206:209], v[134:137]
	v_mfma_f32_16x16x32_bf16 v[118:121], v[190:193], v[214:217], v[118:121]
	v_mfma_f32_16x16x32_bf16 v[102:105], v[190:193], v[222:225], v[102:105]
	v_mfma_f32_16x16x32_bf16 v[70:73], v[190:193], v[230:233], v[70:73]
	v_mfma_f32_16x16x32_bf16 v[66:69], v[198:201], v[230:233], v[66:69]
	v_mfma_f32_16x16x32_bf16 v[98:101], v[198:201], v[222:225], v[98:101]
	v_mfma_f32_16x16x32_bf16 v[114:117], v[198:201], v[214:217], v[114:117]
	v_mfma_f32_16x16x32_bf16 v[130:133], v[198:201], v[206:209], v[130:133]
	s_setprio 0
	s_barrier
	s_add_i32 s52, s42, s37
	v_lshl_add_u64 v[234:235], s[10:11], 0, v[148:149]
	s_mov_b32 m0, s52
	ds_read_b128 v[202:205], v180 offset:16384
	ds_read_b128 v[206:209], v180 offset:17408
	ds_read_b128 v[210:213], v180 offset:18432
	ds_read_b128 v[214:217], v180 offset:19456
	ds_read_b128 v[218:221], v180 offset:20480
	ds_read_b128 v[222:225], v180 offset:21504
	ds_read_b128 v[226:229], v180 offset:22528
	ds_read_b128 v[230:233], v180 offset:23552
	global_load_lds_dwordx4 v[234:235], off
	s_add_i32 m0, s52, 0x2000
	s_add_u32 s52, s10, 0x40000
	v_lshl_add_u64 v[236:237], s[10:11], 0, v[152:153]
	s_addc_u32 s53, s11, 0
	s_add_i32 s54, s43, s37
	global_load_lds_dwordx4 v[236:237], off
	v_lshl_add_u64 v[238:239], s[52:53], 0, v[148:149]
	s_mov_b32 m0, s54
	v_lshl_add_u64 v[240:241], s[34:35], 0, v[150:151]
	global_load_lds_dwordx4 v[238:239], off
	v_lshl_add_u64 v[238:239], s[52:53], 0, v[152:153]
	s_add_i32 m0, s54, 0x2000
	s_nop 0
	global_load_lds_dwordx4 v[238:239], off
	v_lshl_add_u64 v[238:239], s[34:35], 0, v[146:147]
	s_mov_b32 m0, s29
	s_nop 0
	global_load_lds_dwordx4 v[238:239], off
	s_mov_b32 m0, s31
	s_nop 0
	global_load_lds_dwordx4 v[240:241], off
	s_waitcnt vmcnt(8)
	s_waitcnt lgkmcnt(0)
	s_barrier
; #define PG8_STAGE(bufoff, gbase, voff) do { _Pragma("unroll") for (int _i = 0; _i < 2; ++_i) \
;         __builtin_amdgcn_global_load_lds((const unsigned*)((const char*)(gbase) + (voff)[_i]), (PG8_LAS unsigned*)(lds + (bufoff) + ldsw + _i * 8192), 16, 0, 0); } while (0)
; #define PG8_LDA(dst, b, h) do { _Pragma("unroll") for (int m = 0; m < 4; ++m) _Pragma("unroll") for (int k = 0; k < 2; ++k) dst[m][k] = *(const PG8_LAS bf16x8*)(lds + PG8_SA(b, h) + aoff + m * 2048 + k * 1024); } while (0)
; #define PG8_LDB(dst, b, h) do { _Pragma("unroll") for (int n = 0; n < 2; ++n) _Pragma("unroll") for (int k = 0; k < 2; ++k) dst[n][k] = *(const PG8_LAS bf16x8*)(lds + PG8_SB(b, h) + boff + n * 2048 + k * 1024); } while (0)
; #define PG8_MMA(ai, bj, At, Bt) do { __builtin_amdgcn_s_setprio(1); _Pragma("unroll") for (int m = 0; m < 4; ++m) _Pragma("unroll") for (int n = 0; n < 2; ++n) _Pragma("unroll") for (int k = 0; k < 2; ++k) \
;         acc[ai][bj][m][n] = __builtin_amdgcn_mfma_f32_16x16x32_bf16(Bt[n][k], At[m][k], acc[ai][bj][m][n], 0, 0, 0); __builtin_amdgcn_s_setprio(0); } while (0)
; #define PG8_WAIT_V(n) asm volatile("s_waitcnt vmcnt(" #n ")" ::: "memory")
; #define PG8_WAIT_L(n) asm volatile("s_waitcnt lgkmcnt(" #n ")" ::: "memory")
; #define PG8_BAR __builtin_amdgcn_s_barrier()
; #define PG8_SCHED __builtin_amdgcn_sched_barrier(0)
; template <class Epi, class Sched, bool ALIGN_EPI = false, bool SP2 = false>
; __device__ __forceinline__ void gemm_phase(PG8_LAS unsigned char* lds, const Gemm g, const Sched& S, const Epi& E) {
;     ...
;             PG8_WAIT_V(8); PG8_WAIT_L(0); PG8_BAR; PG8_MMA(1, 0, At, B0); PG8_MMA(1, 1, At, B1); PG8_BAR; PG8_SCHED;
;             PG8_LDB(B0, 1, 0); PG8_LDB(B1, 1, 1); PG8_SCHED; PG8_LDA(At, 1, 0); PG8_STAGE(PG8_SA(0, 1), a2 + hstep, voffA);
;             PG8_WAIT_V(8); PG8_WAIT_L(0); PG8_BAR; PG8_MMA(0, 0, At, B0); PG8_MMA(0, 1, At, B1); PG8_BAR; PG8_SCHED;
	s_setprio 1
	s_waitcnt lgkmcnt(0)
	v_mfma_f32_16x16x32_bf16 v[62:65], v[82:85], v[202:205], v[62:65]
	v_mfma_f32_16x16x32_bf16 v[46:49], v[82:85], v[210:213], v[46:49]
	v_mfma_f32_16x16x32_bf16 v[30:33], v[82:85], v[218:221], v[30:33]
	v_mfma_f32_16x16x32_bf16 v[14:17], v[82:85], v[226:229], v[14:17]
	v_mfma_f32_16x16x32_bf16 v[10:13], v[90:93], v[226:229], v[10:13]
	v_mfma_f32_16x16x32_bf16 v[26:29], v[90:93], v[218:221], v[26:29]
	v_mfma_f32_16x16x32_bf16 v[42:45], v[90:93], v[210:213], v[42:45]
	v_mfma_f32_16x16x32_bf16 v[58:61], v[90:93], v[202:205], v[58:61]
	v_mfma_f32_16x16x32_bf16 v[62:65], v[86:89], v[206:209], v[62:65]
	v_mfma_f32_16x16x32_bf16 v[46:49], v[86:89], v[214:217], v[46:49]
	v_mfma_f32_16x16x32_bf16 v[30:33], v[86:89], v[222:225], v[30:33]
	v_mfma_f32_16x16x32_bf16 v[14:17], v[86:89], v[230:233], v[14:17]
	v_mfma_f32_16x16x32_bf16 v[10:13], v[94:97], v[230:233], v[10:13]
	v_mfma_f32_16x16x32_bf16 v[26:29], v[94:97], v[222:225], v[26:29]
	v_mfma_f32_16x16x32_bf16 v[42:45], v[94:97], v[214:217], v[42:45]
	v_mfma_f32_16x16x32_bf16 v[58:61], v[94:97], v[206:209], v[58:61]
	s_setprio 0
	s_setprio 1
	v_mfma_f32_16x16x32_bf16 v[54:57], v[186:189], v[202:205], v[54:57]
	v_mfma_f32_16x16x32_bf16 v[38:41], v[186:189], v[210:213], v[38:41]
	v_mfma_f32_16x16x32_bf16 v[22:25], v[186:189], v[218:221], v[22:25]
	v_mfma_f32_16x16x32_bf16 v[6:9], v[186:189], v[226:229], v[6:9]
	v_mfma_f32_16x16x32_bf16 v[2:5], v[194:197], v[226:229], v[2:5]
	v_mfma_f32_16x16x32_bf16 v[18:21], v[194:197], v[218:221], v[18:21]
	v_mfma_f32_16x16x32_bf16 v[34:37], v[194:197], v[210:213], v[34:37]
	v_mfma_f32_16x16x32_bf16 v[50:53], v[194:197], v[202:205], v[50:53]
	v_mfma_f32_16x16x32_bf16 v[54:57], v[190:193], v[206:209], v[54:57]
	v_mfma_f32_16x16x32_bf16 v[38:41], v[190:193], v[214:217], v[38:41]
	v_mfma_f32_16x16x32_bf16 v[22:25], v[190:193], v[222:225], v[22:25]
	v_mfma_f32_16x16x32_bf16 v[6:9], v[190:193], v[230:233], v[6:9]
	v_mfma_f32_16x16x32_bf16 v[2:5], v[198:201], v[230:233], v[2:5]
	v_mfma_f32_16x16x32_bf16 v[18:21], v[198:201], v[222:225], v[18:21]
	v_mfma_f32_16x16x32_bf16 v[34:37], v[198:201], v[214:217], v[34:37]
	v_mfma_f32_16x16x32_bf16 v[50:53], v[198:201], v[206:209], v[50:53]
	s_setprio 0
	s_barrier
	s_add_i32 s52, 0, 0x18000
	s_add_i32 s53, 0, 0x1c000
	v_add_u32_e32 v94, s52, v1
	v_add_u32_e32 v167, s53, v1
	ds_read_b128 v[82:85], v94
	ds_read_b128 v[86:89], v94 offset:1024
	ds_read_b128 v[90:93], v94 offset:2048
	ds_read_b128 v[94:97], v94 offset:3072
	ds_read_b128 v[186:189], v167
	ds_read_b128 v[190:193], v167 offset:1024
	ds_read_b128 v[194:197], v167 offset:2048
	ds_read_b128 v[198:201], v167 offset:3072
	s_add_u32 s34, s34, 0x100000
	s_addc_u32 s35, s35, 0
	s_mov_b32 m0, s38
	v_lshl_add_u64 v[242:243], s[34:35], 0, v[146:147]
	ds_read_b128 v[202:205], v180 offset:32768
	ds_read_b128 v[206:209], v180 offset:33792
	ds_read_b128 v[210:213], v180 offset:34816
	ds_read_b128 v[214:217], v180 offset:35840
	ds_read_b128 v[218:221], v180 offset:36864
	ds_read_b128 v[222:225], v180 offset:37888
	ds_read_b128 v[226:229], v180 offset:38912
	ds_read_b128 v[230:233], v180 offset:39936
	global_load_lds_dwordx4 v[242:243], off
	v_lshl_add_u64 v[242:243], s[34:35], 0, v[150:151]
	s_mov_b32 m0, s39
	s_nop 0
	global_load_lds_dwordx4 v[242:243], off
	s_waitcnt vmcnt(8)
	s_waitcnt lgkmcnt(0)
	s_barrier
	s_setprio 1
	s_waitcnt lgkmcnt(0)
	v_mfma_f32_16x16x32_bf16 v[142:145], v[82:85], v[202:205], v[142:145]
	v_mfma_f32_16x16x32_bf16 v[126:129], v[82:85], v[210:213], v[126:129]
	v_mfma_f32_16x16x32_bf16 v[110:113], v[82:85], v[218:221], v[110:113]
	v_mfma_f32_16x16x32_bf16 v[78:81], v[82:85], v[226:229], v[78:81]
	v_mfma_f32_16x16x32_bf16 v[74:77], v[90:93], v[226:229], v[74:77]
	v_mfma_f32_16x16x32_bf16 v[106:109], v[90:93], v[218:221], v[106:109]
	v_mfma_f32_16x16x32_bf16 v[122:125], v[90:93], v[210:213], v[122:125]
	v_mfma_f32_16x16x32_bf16 v[138:141], v[90:93], v[202:205], v[138:141]
	v_mfma_f32_16x16x32_bf16 v[142:145], v[86:89], v[206:209], v[142:145]
	v_mfma_f32_16x16x32_bf16 v[126:129], v[86:89], v[214:217], v[126:129]
	v_mfma_f32_16x16x32_bf16 v[110:113], v[86:89], v[222:225], v[110:113]
	v_mfma_f32_16x16x32_bf16 v[78:81], v[86:89], v[230:233], v[78:81]
	v_mfma_f32_16x16x32_bf16 v[74:77], v[94:97], v[230:233], v[74:77]
	v_mfma_f32_16x16x32_bf16 v[106:109], v[94:97], v[222:225], v[106:109]
	v_mfma_f32_16x16x32_bf16 v[122:125], v[94:97], v[214:217], v[122:125]
	v_mfma_f32_16x16x32_bf16 v[138:141], v[94:97], v[206:209], v[138:141]
	s_setprio 0
	s_setprio 1
	v_mfma_f32_16x16x32_bf16 v[134:137], v[186:189], v[202:205], v[134:137]
	v_mfma_f32_16x16x32_bf16 v[118:121], v[186:189], v[210:213], v[118:121]
	v_mfma_f32_16x16x32_bf16 v[102:105], v[186:189], v[218:221], v[102:105]
	v_mfma_f32_16x16x32_bf16 v[70:73], v[186:189], v[226:229], v[70:73]
	v_mfma_f32_16x16x32_bf16 v[66:69], v[194:197], v[226:229], v[66:69]
	v_mfma_f32_16x16x32_bf16 v[98:101], v[194:197], v[218:221], v[98:101]
	v_mfma_f32_16x16x32_bf16 v[114:117], v[194:197], v[210:213], v[114:117]
	v_mfma_f32_16x16x32_bf16 v[130:133], v[194:197], v[202:205], v[130:133]
	v_mfma_f32_16x16x32_bf16 v[134:137], v[190:193], v[206:209], v[134:137]
	v_mfma_f32_16x16x32_bf16 v[118:121], v[190:193], v[214:217], v[118:121]
	v_mfma_f32_16x16x32_bf16 v[102:105], v[190:193], v[222:225], v[102:105]
	v_mfma_f32_16x16x32_bf16 v[70:73], v[190:193], v[230:233], v[70:73]
	v_mfma_f32_16x16x32_bf16 v[66:69], v[198:201], v[230:233], v[66:69]
	v_mfma_f32_16x16x32_bf16 v[98:101], v[198:201], v[222:225], v[98:101]
	v_mfma_f32_16x16x32_bf16 v[114:117], v[198:201], v[214:217], v[114:117]
	v_mfma_f32_16x16x32_bf16 v[130:133], v[198:201], v[206:209], v[130:133]
	s_setprio 0
	s_barrier
; #define PG8_STAGE(bufoff, gbase, voff) do { _Pragma("unroll") for (int _i = 0; _i < 2; ++_i) \
;         __builtin_amdgcn_global_load_lds((const unsigned*)((const char*)(gbase) + (voff)[_i]), (PG8_LAS unsigned*)(lds + (bufoff) + ldsw + _i * 8192), 16, 0, 0); } while (0)
; #define PG8_LDA(dst, b, h) do { _Pragma("unroll") for (int m = 0; m < 4; ++m) _Pragma("unroll") for (int k = 0; k < 2; ++k) dst[m][k] = *(const PG8_LAS bf16x8*)(lds + PG8_SA(b, h) + aoff + m * 2048 + k * 1024); } while (0)
; #define PG8_MMA(ai, bj, At, Bt) do { __builtin_amdgcn_s_setprio(1); _Pragma("unroll") for (int m = 0; m < 4; ++m) _Pragma("unroll") for (int n = 0; n < 2; ++n) _Pragma("unroll") for (int k = 0; k < 2; ++k) \
;         acc[ai][bj][m][n] = __builtin_amdgcn_mfma_f32_16x16x32_bf16(Bt[n][k], At[m][k], acc[ai][bj][m][n], 0, 0, 0); __builtin_amdgcn_s_setprio(0); } while (0)
; #define PG8_WAIT_V(n) asm volatile("s_waitcnt vmcnt(" #n ")" ::: "memory")
; #define PG8_WAIT_L(n) asm volatile("s_waitcnt lgkmcnt(" #n ")" ::: "memory")
; #define PG8_BAR __builtin_amdgcn_s_barrier()
; #define PG8_SCHED __builtin_amdgcn_sched_barrier(0)
; template <class Epi, class Sched, bool ALIGN_EPI = false, bool SP2 = false>
; __device__ __forceinline__ void gemm_phase(PG8_LAS unsigned char* lds, const Gemm g, const Sched& S, const Epi& E) {
;     ...
;             PG8_LDA(At, 1, 1); PG8_STAGE(PG8_SB(1, 0), b3, voffB); PG8_STAGE(PG8_SB(1, 1), b3 + hstepB, voffB); PG8_STAGE(PG8_SA(1, 0), a3, voffA);
;             PG8_WAIT_V(8); PG8_WAIT_L(0); PG8_BAR; PG8_MMA(1, 0, At, B0); PG8_MMA(1, 1, At, B1); PG8_BAR; PG8_SCHED;
	s_add_i32 s34, s52, s37
	v_lshl_add_u64 v[234:235], v[234:235], 0, s[16:17]
	s_mov_b32 m0, s34
	ds_read_b128 v[202:205], v180 offset:49152
	ds_read_b128 v[206:209], v180 offset:50176
	ds_read_b128 v[210:213], v180 offset:51200
	ds_read_b128 v[214:217], v180 offset:52224
	ds_read_b128 v[218:221], v180 offset:53248
	ds_read_b128 v[222:225], v180 offset:54272
	ds_read_b128 v[226:229], v180 offset:55296
	ds_read_b128 v[230:233], v180 offset:56320
	global_load_lds_dwordx4 v[234:235], off
	s_add_i32 m0, s34, 0x2000
	s_add_u32 s10, s10, 0x40080
	v_lshl_add_u64 v[234:235], v[236:237], 0, s[16:17]
	s_addc_u32 s11, s11, 0
	s_add_i32 s34, s53, s37
	global_load_lds_dwordx4 v[234:235], off
	v_lshl_add_u64 v[234:235], s[10:11], 0, v[148:149]
	s_mov_b32 m0, s34
	s_nop 0
	global_load_lds_dwordx4 v[234:235], off
	v_lshl_add_u64 v[234:235], s[10:11], 0, v[152:153]
	s_add_i32 m0, s34, 0x2000
	s_nop 0
	global_load_lds_dwordx4 v[234:235], off
	v_lshl_add_u64 v[234:235], v[238:239], 0, s[16:17]
	s_mov_b32 m0, s40
	s_nop 0
	global_load_lds_dwordx4 v[234:235], off
	v_lshl_add_u64 v[234:235], v[240:241], 0, s[16:17]
	s_mov_b32 m0, s41
	s_nop 0
	global_load_lds_dwordx4 v[234:235], off
	s_waitcnt vmcnt(8)
	s_waitcnt lgkmcnt(0)
	s_barrier
	s_setprio 1
	s_waitcnt lgkmcnt(0)
	v_mfma_f32_16x16x32_bf16 v[62:65], v[82:85], v[202:205], v[62:65]
	v_mfma_f32_16x16x32_bf16 v[46:49], v[82:85], v[210:213], v[46:49]
	v_mfma_f32_16x16x32_bf16 v[30:33], v[82:85], v[218:221], v[30:33]
	v_mfma_f32_16x16x32_bf16 v[14:17], v[82:85], v[226:229], v[14:17]
	v_mfma_f32_16x16x32_bf16 v[10:13], v[90:93], v[226:229], v[10:13]
	v_mfma_f32_16x16x32_bf16 v[26:29], v[90:93], v[218:221], v[26:29]
	v_mfma_f32_16x16x32_bf16 v[42:45], v[90:93], v[210:213], v[42:45]
	v_mfma_f32_16x16x32_bf16 v[58:61], v[90:93], v[202:205], v[58:61]
	v_mfma_f32_16x16x32_bf16 v[62:65], v[86:89], v[206:209], v[62:65]
	v_mfma_f32_16x16x32_bf16 v[46:49], v[86:89], v[214:217], v[46:49]
	v_mfma_f32_16x16x32_bf16 v[30:33], v[86:89], v[222:225], v[30:33]
	v_mfma_f32_16x16x32_bf16 v[14:17], v[86:89], v[230:233], v[14:17]
	v_mfma_f32_16x16x32_bf16 v[10:13], v[94:97], v[230:233], v[10:13]
	v_mfma_f32_16x16x32_bf16 v[26:29], v[94:97], v[222:225], v[26:29]
	v_mfma_f32_16x16x32_bf16 v[42:45], v[94:97], v[214:217], v[42:45]
	v_mfma_f32_16x16x32_bf16 v[58:61], v[94:97], v[206:209], v[58:61]
	s_setprio 0
	s_setprio 1
	v_mfma_f32_16x16x32_bf16 v[54:57], v[186:189], v[202:205], v[54:57]
	v_mfma_f32_16x16x32_bf16 v[38:41], v[186:189], v[210:213], v[38:41]
	v_mfma_f32_16x16x32_bf16 v[22:25], v[186:189], v[218:221], v[22:25]
	v_mfma_f32_16x16x32_bf16 v[6:9], v[186:189], v[226:229], v[6:9]
	v_mfma_f32_16x16x32_bf16 v[2:5], v[194:197], v[226:229], v[2:5]
	v_mfma_f32_16x16x32_bf16 v[18:21], v[194:197], v[218:221], v[18:21]
	v_mfma_f32_16x16x32_bf16 v[34:37], v[194:197], v[210:213], v[34:37]
	v_mfma_f32_16x16x32_bf16 v[50:53], v[194:197], v[202:205], v[50:53]
	v_mfma_f32_16x16x32_bf16 v[54:57], v[190:193], v[206:209], v[54:57]
	v_mfma_f32_16x16x32_bf16 v[38:41], v[190:193], v[214:217], v[38:41]
	v_mfma_f32_16x16x32_bf16 v[22:25], v[190:193], v[222:225], v[22:25]
	v_mfma_f32_16x16x32_bf16 v[6:9], v[190:193], v[230:233], v[6:9]
	v_mfma_f32_16x16x32_bf16 v[2:5], v[198:201], v[230:233], v[2:5]
	v_mfma_f32_16x16x32_bf16 v[18:21], v[198:201], v[222:225], v[18:21]
	v_mfma_f32_16x16x32_bf16 v[34:37], v[198:201], v[214:217], v[34:37]
	v_mfma_f32_16x16x32_bf16 v[50:53], v[198:201], v[206:209], v[50:53]
	s_setprio 0
	s_barrier
	s_add_i32 s51, s51, 2
	s_add_u32 s6, s6, 0x100
	s_addc_u32 s7, s7, 0
	s_add_u32 s49, s49, 0x100
	s_addc_u32 s50, s50, 0
	s_cmp_gt_u32 s51, 61
	s_cbranch_scc0 .LBB0_402
	s_and_b64 vcc, exec, s[18:19]
	s_cbranch_vccz .LBB0_405
	s_barrier

; #define PG8_STAGE(bufoff, gbase, voff) do { _Pragma("unroll") for (int _i = 0; _i < 2; ++_i) \
;         __builtin_amdgcn_global_load_lds((const unsigned*)((const char*)(gbase) + (voff)[_i]), (PG8_LAS unsigned*)(lds + (bufoff) + ldsw + _i * 8192), 16, 0, 0); } while (0)
; #define PG8_LDA(dst, b, h) do { _Pragma("unroll") for (int m = 0; m < 4; ++m) _Pragma("unroll") for (int k = 0; k < 2; ++k) dst[m][k] = *(const PG8_LAS bf16x8*)(lds + PG8_SA(b, h) + aoff + m * 2048 + k * 1024); } while (0)
; #define PG8_LDB(dst, b, h) do { _Pragma("unroll") for (int n = 0; n < 2; ++n) _Pragma("unroll") for (int k = 0; k < 2; ++k) dst[n][k] = *(const PG8_LAS bf16x8*)(lds + PG8_SB(b, h) + boff + n * 2048 + k * 1024); } while (0)
; #define PG8_MMA(ai, bj, At, Bt) do { __builtin_amdgcn_s_setprio(1); _Pragma("unroll") for (int m = 0; m < 4; ++m) _Pragma("unroll") for (int n = 0; n < 2; ++n) _Pragma("unroll") for (int k = 0; k < 2; ++k) \
;         acc[ai][bj][m][n] = __builtin_amdgcn_mfma_f32_16x16x32_bf16(Bt[n][k], At[m][k], acc[ai][bj][m][n], 0, 0, 0); __builtin_amdgcn_s_setprio(0); } while (0)
; #define PG8_WAIT_V(n) asm volatile("s_waitcnt vmcnt(" #n ")" ::: "memory")
; #define PG8_WAIT_L(n) asm volatile("s_waitcnt lgkmcnt(" #n ")" ::: "memory")
; #define PG8_BAR __builtin_amdgcn_s_barrier()
; #define PG8_SCHED __builtin_amdgcn_sched_barrier(0)
; template <class Epi, class Sched, bool ALIGN_EPI = false, bool SP2 = false>
; __device__ __forceinline__ void gemm_phase(PG8_LAS unsigned char* lds, const Gemm g, const Sched& S, const Epi& E) {
;     ...
;             PG8_LDB(B0, 0, 0); PG8_LDB(B1, 0, 1); PG8_SCHED; PG8_LDA(At, 0, 0); PG8_STAGE(PG8_SA(1, 1), a1 + hstep, voffA);
;             PG8_WAIT_V(8); PG8_WAIT_L(0); PG8_BAR; PG8_MMA(0, 0, At, B0); PG8_MMA(0, 1, At, B1); PG8_BAR; PG8_SCHED;
;             PG8_LDA(At, 0, 1); PG8_STAGE(PG8_SB(0, 0), b2, voffB); PG8_STAGE(PG8_SB(0, 1), b2 + hstepB, voffB); PG8_STAGE(PG8_SA(0, 0), a2, voffA);
;             PG8_WAIT_V(8); PG8_WAIT_L(0); PG8_BAR; PG8_MMA(1, 0, At, B0); PG8_MMA(1, 1, At, B1); PG8_BAR; PG8_SCHED;
.LBB0_1759:
	ds_read_b128 v[66:69], v168
	ds_read_b128 v[70:73], v168 offset:1024
	ds_read_b128 v[74:77], v168 offset:2048
	ds_read_b128 v[78:81], v168 offset:3072
	ds_read_b128 v[162:165], v169
	ds_read_b128 v[172:175], v169 offset:1024
	ds_read_b128 v[176:179], v169 offset:2048
	ds_read_b128 v[180:183], v169 offset:3072
	s_add_u32 s34, s30, 0xfff00080
	s_addc_u32 s35, s31, -1
	s_cmp_eq_u32 s63, 60
	s_cselect_b32 s37, s23, s35
	s_cselect_b32 s36, s59, s34
	s_cselect_b32 s35, s21, s62
	s_cselect_b32 s34, s60, s61
	v_lshl_add_u64 v[216:217], s[30:31], 0, v[154:155]
	s_add_i32 m0, s40, 0xc000
	ds_read_b128 v[184:187], v170
	ds_read_b128 v[188:191], v170 offset:1024
	ds_read_b128 v[192:195], v170 offset:2048
	ds_read_b128 v[196:199], v170 offset:3072
	ds_read_b128 v[200:203], v170 offset:4096
	ds_read_b128 v[204:207], v170 offset:5120
	ds_read_b128 v[208:211], v170 offset:6144
	ds_read_b128 v[212:215], v170 offset:7168
	global_load_lds_dwordx4 v[216:217], off
	v_lshl_add_u64 v[216:217], s[30:31], 0, v[156:157]
	s_add_i32 m0, s40, 0xe000
	s_nop 0
	global_load_lds_dwordx4 v[216:217], off
	s_waitcnt vmcnt(8)
	s_waitcnt lgkmcnt(0)
	s_barrier
	s_setprio 1
	s_waitcnt lgkmcnt(0)
	v_mfma_f32_16x16x32_bf16 v[142:145], v[66:69], v[184:187], v[142:145]
	v_mfma_f32_16x16x32_bf16 v[126:129], v[66:69], v[192:195], v[126:129]
	v_mfma_f32_16x16x32_bf16 v[110:113], v[66:69], v[200:203], v[110:113]
	v_mfma_f32_16x16x32_bf16 v[94:97], v[66:69], v[208:211], v[94:97]
	v_mfma_f32_16x16x32_bf16 v[90:93], v[74:77], v[208:211], v[90:93]
	v_mfma_f32_16x16x32_bf16 v[106:109], v[74:77], v[200:203], v[106:109]
	v_mfma_f32_16x16x32_bf16 v[122:125], v[74:77], v[192:195], v[122:125]
	v_mfma_f32_16x16x32_bf16 v[138:141], v[74:77], v[184:187], v[138:141]
	v_mfma_f32_16x16x32_bf16 v[142:145], v[70:73], v[188:191], v[142:145]
	v_mfma_f32_16x16x32_bf16 v[126:129], v[70:73], v[196:199], v[126:129]
	v_mfma_f32_16x16x32_bf16 v[110:113], v[70:73], v[204:207], v[110:113]
	v_mfma_f32_16x16x32_bf16 v[94:97], v[70:73], v[212:215], v[94:97]
	v_mfma_f32_16x16x32_bf16 v[90:93], v[78:81], v[212:215], v[90:93]
	v_mfma_f32_16x16x32_bf16 v[106:109], v[78:81], v[204:207], v[106:109]
	v_mfma_f32_16x16x32_bf16 v[122:125], v[78:81], v[196:199], v[122:125]
	v_mfma_f32_16x16x32_bf16 v[138:141], v[78:81], v[188:191], v[138:141]
	s_setprio 0
	s_setprio 1
	v_mfma_f32_16x16x32_bf16 v[134:137], v[162:165], v[184:187], v[134:137]
	v_mfma_f32_16x16x32_bf16 v[118:121], v[162:165], v[192:195], v[118:121]
	v_mfma_f32_16x16x32_bf16 v[102:105], v[162:165], v[200:203], v[102:105]
	v_mfma_f32_16x16x32_bf16 v[86:89], v[162:165], v[208:211], v[86:89]
	v_mfma_f32_16x16x32_bf16 v[82:85], v[176:179], v[208:211], v[82:85]
	v_mfma_f32_16x16x32_bf16 v[98:101], v[176:179], v[200:203], v[98:101]
	v_mfma_f32_16x16x32_bf16 v[114:117], v[176:179], v[192:195], v[114:117]
	v_mfma_f32_16x16x32_bf16 v[130:133], v[176:179], v[184:187], v[130:133]
	v_mfma_f32_16x16x32_bf16 v[134:137], v[172:175], v[188:191], v[134:137]
	v_mfma_f32_16x16x32_bf16 v[118:121], v[172:175], v[196:199], v[118:121]
	v_mfma_f32_16x16x32_bf16 v[102:105], v[172:175], v[204:207], v[102:105]
	v_mfma_f32_16x16x32_bf16 v[86:89], v[172:175], v[212:215], v[86:89]
	v_mfma_f32_16x16x32_bf16 v[82:85], v[180:183], v[212:215], v[82:85]
	v_mfma_f32_16x16x32_bf16 v[98:101], v[180:183], v[204:207], v[98:101]
	v_mfma_f32_16x16x32_bf16 v[114:117], v[180:183], v[196:199], v[114:117]
	v_mfma_f32_16x16x32_bf16 v[130:133], v[180:183], v[188:191], v[130:133]
	s_setprio 0
	s_barrier
	s_add_i32 s64, s50, s39
	v_lshl_add_u64 v[216:217], s[34:35], 0, v[148:149]
	s_mov_b32 m0, s64
	ds_read_b128 v[184:187], v170 offset:16384
	ds_read_b128 v[188:191], v170 offset:17408
	ds_read_b128 v[192:195], v170 offset:18432
	ds_read_b128 v[196:199], v170 offset:19456
	ds_read_b128 v[200:203], v170 offset:20480
	ds_read_b128 v[204:207], v170 offset:21504
	ds_read_b128 v[208:211], v170 offset:22528
	ds_read_b128 v[212:215], v170 offset:23552
	global_load_lds_dwordx4 v[216:217], off
	s_add_i32 m0, s64, 0x2000
	s_add_u32 s64, s34, 0x100000
	v_lshl_add_u64 v[218:219], s[34:35], 0, v[152:153]
	s_addc_u32 s65, s35, 0
	s_add_i32 s66, s51, s39
	global_load_lds_dwordx4 v[218:219], off
	v_lshl_add_u64 v[220:221], s[64:65], 0, v[148:149]
	s_mov_b32 m0, s66
	v_lshl_add_u64 v[222:223], s[36:37], 0, v[150:151]
	global_load_lds_dwordx4 v[220:221], off
	v_lshl_add_u64 v[220:221], s[64:65], 0, v[152:153]
	s_add_i32 m0, s66, 0x2000
	s_nop 0
	global_load_lds_dwordx4 v[220:221], off
	v_lshl_add_u64 v[220:221], s[36:37], 0, v[146:147]
	s_mov_b32 m0, s40
	s_nop 0
	global_load_lds_dwordx4 v[220:221], off
	s_mov_b32 m0, s41
	s_nop 0
	global_load_lds_dwordx4 v[222:223], off
	s_waitcnt vmcnt(8)
	s_waitcnt lgkmcnt(0)
	s_barrier
; #define PG8_STAGE(bufoff, gbase, voff) do { _Pragma("unroll") for (int _i = 0; _i < 2; ++_i) \
;         __builtin_amdgcn_global_load_lds((const unsigned*)((const char*)(gbase) + (voff)[_i]), (PG8_LAS unsigned*)(lds + (bufoff) + ldsw + _i * 8192), 16, 0, 0); } while (0)
; #define PG8_LDA(dst, b, h) do { _Pragma("unroll") for (int m = 0; m < 4; ++m) _Pragma("unroll") for (int k = 0; k < 2; ++k) dst[m][k] = *(const PG8_LAS bf16x8*)(lds + PG8_SA(b, h) + aoff + m * 2048 + k * 1024); } while (0)
; #define PG8_LDB(dst, b, h) do { _Pragma("unroll") for (int n = 0; n < 2; ++n) _Pragma("unroll") for (int k = 0; k < 2; ++k) dst[n][k] = *(const PG8_LAS bf16x8*)(lds + PG8_SB(b, h) + boff + n * 2048 + k * 1024); } while (0)
; #define PG8_MMA(ai, bj, At, Bt) do { __builtin_amdgcn_s_setprio(1); _Pragma("unroll") for (int m = 0; m < 4; ++m) _Pragma("unroll") for (int n = 0; n < 2; ++n) _Pragma("unroll") for (int k = 0; k < 2; ++k) \
;         acc[ai][bj][m][n] = __builtin_amdgcn_mfma_f32_16x16x32_bf16(Bt[n][k], At[m][k], acc[ai][bj][m][n], 0, 0, 0); __builtin_amdgcn_s_setprio(0); } while (0)
; #define PG8_WAIT_V(n) asm volatile("s_waitcnt vmcnt(" #n ")" ::: "memory")
; #define PG8_WAIT_L(n) asm volatile("s_waitcnt lgkmcnt(" #n ")" ::: "memory")
; #define PG8_BAR __builtin_amdgcn_s_barrier()
; #define PG8_SCHED __builtin_amdgcn_sched_barrier(0)
; template <class Epi, class Sched, bool ALIGN_EPI = false, bool SP2 = false>
; __device__ __forceinline__ void gemm_phase(PG8_LAS unsigned char* lds, const Gemm g, const Sched& S, const Epi& E) {
;     ...
;             PG8_WAIT_V(8); PG8_WAIT_L(0); PG8_BAR; PG8_MMA(1, 0, At, B0); PG8_MMA(1, 1, At, B1); PG8_BAR; PG8_SCHED;
;             PG8_LDB(B0, 1, 0); PG8_LDB(B1, 1, 1); PG8_SCHED; PG8_LDA(At, 1, 0); PG8_STAGE(PG8_SA(0, 1), a2 + hstep, voffA);
;             PG8_WAIT_V(8); PG8_WAIT_L(0); PG8_BAR; PG8_MMA(0, 0, At, B0); PG8_MMA(0, 1, At, B1); PG8_BAR; PG8_SCHED;
	s_setprio 1
	s_waitcnt lgkmcnt(0)
	v_mfma_f32_16x16x32_bf16 v[62:65], v[66:69], v[184:187], v[62:65]
	v_mfma_f32_16x16x32_bf16 v[46:49], v[66:69], v[192:195], v[46:49]
	v_mfma_f32_16x16x32_bf16 v[30:33], v[66:69], v[200:203], v[30:33]
	v_mfma_f32_16x16x32_bf16 v[22:25], v[66:69], v[208:211], v[22:25]
	v_mfma_f32_16x16x32_bf16 v[18:21], v[74:77], v[208:211], v[18:21]
	v_mfma_f32_16x16x32_bf16 v[26:29], v[74:77], v[200:203], v[26:29]
	v_mfma_f32_16x16x32_bf16 v[42:45], v[74:77], v[192:195], v[42:45]
	v_mfma_f32_16x16x32_bf16 v[58:61], v[74:77], v[184:187], v[58:61]
	v_mfma_f32_16x16x32_bf16 v[62:65], v[70:73], v[188:191], v[62:65]
	v_mfma_f32_16x16x32_bf16 v[46:49], v[70:73], v[196:199], v[46:49]
	v_mfma_f32_16x16x32_bf16 v[30:33], v[70:73], v[204:207], v[30:33]
	v_mfma_f32_16x16x32_bf16 v[22:25], v[70:73], v[212:215], v[22:25]
	v_mfma_f32_16x16x32_bf16 v[18:21], v[78:81], v[212:215], v[18:21]
	v_mfma_f32_16x16x32_bf16 v[26:29], v[78:81], v[204:207], v[26:29]
	v_mfma_f32_16x16x32_bf16 v[42:45], v[78:81], v[196:199], v[42:45]
	v_mfma_f32_16x16x32_bf16 v[58:61], v[78:81], v[188:191], v[58:61]
	s_setprio 0
	s_setprio 1
	v_mfma_f32_16x16x32_bf16 v[54:57], v[162:165], v[184:187], v[54:57]
	v_mfma_f32_16x16x32_bf16 v[38:41], v[162:165], v[192:195], v[38:41]
	v_mfma_f32_16x16x32_bf16 v[14:17], v[162:165], v[200:203], v[14:17]
	v_mfma_f32_16x16x32_bf16 v[6:9], v[162:165], v[208:211], v[6:9]
	v_mfma_f32_16x16x32_bf16 v[2:5], v[176:179], v[208:211], v[2:5]
	v_mfma_f32_16x16x32_bf16 v[10:13], v[176:179], v[200:203], v[10:13]
	v_mfma_f32_16x16x32_bf16 v[34:37], v[176:179], v[192:195], v[34:37]
	v_mfma_f32_16x16x32_bf16 v[50:53], v[176:179], v[184:187], v[50:53]
	v_mfma_f32_16x16x32_bf16 v[54:57], v[172:175], v[188:191], v[54:57]
	v_mfma_f32_16x16x32_bf16 v[38:41], v[172:175], v[196:199], v[38:41]
	v_mfma_f32_16x16x32_bf16 v[14:17], v[172:175], v[204:207], v[14:17]
	v_mfma_f32_16x16x32_bf16 v[6:9], v[172:175], v[212:215], v[6:9]
	v_mfma_f32_16x16x32_bf16 v[2:5], v[180:183], v[212:215], v[2:5]
	v_mfma_f32_16x16x32_bf16 v[10:13], v[180:183], v[204:207], v[10:13]
	v_mfma_f32_16x16x32_bf16 v[34:37], v[180:183], v[196:199], v[34:37]
	v_mfma_f32_16x16x32_bf16 v[50:53], v[180:183], v[188:191], v[50:53]
	s_setprio 0
	s_barrier
	s_add_i32 s64, 0, 0x18000
	s_add_i32 s65, 0, 0x1c000
	v_add_u32_e32 v78, s64, v166
	v_add_u32_e32 v171, s65, v166
	ds_read_b128 v[66:69], v78
	ds_read_b128 v[70:73], v78 offset:1024
	ds_read_b128 v[74:77], v78 offset:2048
	ds_read_b128 v[78:81], v78 offset:3072
	ds_read_b128 v[162:165], v171
	ds_read_b128 v[172:175], v171 offset:1024
	ds_read_b128 v[176:179], v171 offset:2048
	ds_read_b128 v[180:183], v171 offset:3072
	s_add_u32 s36, s36, 0x100000
	s_addc_u32 s37, s37, 0
	s_mov_b32 m0, s42
	v_lshl_add_u64 v[224:225], s[36:37], 0, v[146:147]
	ds_read_b128 v[184:187], v170 offset:32768
	ds_read_b128 v[188:191], v170 offset:33792
	ds_read_b128 v[192:195], v170 offset:34816
	ds_read_b128 v[196:199], v170 offset:35840
	ds_read_b128 v[200:203], v170 offset:36864
	ds_read_b128 v[204:207], v170 offset:37888
	ds_read_b128 v[208:211], v170 offset:38912
	ds_read_b128 v[212:215], v170 offset:39936
	global_load_lds_dwordx4 v[224:225], off
	v_lshl_add_u64 v[224:225], s[36:37], 0, v[150:151]
	s_mov_b32 m0, s43
	s_nop 0
	global_load_lds_dwordx4 v[224:225], off
	s_waitcnt vmcnt(8)
	s_waitcnt lgkmcnt(0)
	s_barrier
	s_setprio 1
	s_waitcnt lgkmcnt(0)
	v_mfma_f32_16x16x32_bf16 v[142:145], v[66:69], v[184:187], v[142:145]
	v_mfma_f32_16x16x32_bf16 v[126:129], v[66:69], v[192:195], v[126:129]
	v_mfma_f32_16x16x32_bf16 v[110:113], v[66:69], v[200:203], v[110:113]
	v_mfma_f32_16x16x32_bf16 v[94:97], v[66:69], v[208:211], v[94:97]
	v_mfma_f32_16x16x32_bf16 v[90:93], v[74:77], v[208:211], v[90:93]
	v_mfma_f32_16x16x32_bf16 v[106:109], v[74:77], v[200:203], v[106:109]
	v_mfma_f32_16x16x32_bf16 v[122:125], v[74:77], v[192:195], v[122:125]
	v_mfma_f32_16x16x32_bf16 v[138:141], v[74:77], v[184:187], v[138:141]
	v_mfma_f32_16x16x32_bf16 v[142:145], v[70:73], v[188:191], v[142:145]
	v_mfma_f32_16x16x32_bf16 v[126:129], v[70:73], v[196:199], v[126:129]
	v_mfma_f32_16x16x32_bf16 v[110:113], v[70:73], v[204:207], v[110:113]
	v_mfma_f32_16x16x32_bf16 v[94:97], v[70:73], v[212:215], v[94:97]
	v_mfma_f32_16x16x32_bf16 v[90:93], v[78:81], v[212:215], v[90:93]
	v_mfma_f32_16x16x32_bf16 v[106:109], v[78:81], v[204:207], v[106:109]
	v_mfma_f32_16x16x32_bf16 v[122:125], v[78:81], v[196:199], v[122:125]
	v_mfma_f32_16x16x32_bf16 v[138:141], v[78:81], v[188:191], v[138:141]
	s_setprio 0
	s_setprio 1
	v_mfma_f32_16x16x32_bf16 v[134:137], v[162:165], v[184:187], v[134:137]
	v_mfma_f32_16x16x32_bf16 v[118:121], v[162:165], v[192:195], v[118:121]
	v_mfma_f32_16x16x32_bf16 v[102:105], v[162:165], v[200:203], v[102:105]
	v_mfma_f32_16x16x32_bf16 v[86:89], v[162:165], v[208:211], v[86:89]
	v_mfma_f32_16x16x32_bf16 v[82:85], v[176:179], v[208:211], v[82:85]
	v_mfma_f32_16x16x32_bf16 v[98:101], v[176:179], v[200:203], v[98:101]
	v_mfma_f32_16x16x32_bf16 v[114:117], v[176:179], v[192:195], v[114:117]
	v_mfma_f32_16x16x32_bf16 v[130:133], v[176:179], v[184:187], v[130:133]
	v_mfma_f32_16x16x32_bf16 v[134:137], v[172:175], v[188:191], v[134:137]
	v_mfma_f32_16x16x32_bf16 v[118:121], v[172:175], v[196:199], v[118:121]
	v_mfma_f32_16x16x32_bf16 v[102:105], v[172:175], v[204:207], v[102:105]
	v_mfma_f32_16x16x32_bf16 v[86:89], v[172:175], v[212:215], v[86:89]
	v_mfma_f32_16x16x32_bf16 v[82:85], v[180:183], v[212:215], v[82:85]
	v_mfma_f32_16x16x32_bf16 v[98:101], v[180:183], v[204:207], v[98:101]
	v_mfma_f32_16x16x32_bf16 v[114:117], v[180:183], v[196:199], v[114:117]
	v_mfma_f32_16x16x32_bf16 v[130:133], v[180:183], v[188:191], v[130:133]
	s_setprio 0
	s_barrier
; #define PG8_STAGE(bufoff, gbase, voff) do { _Pragma("unroll") for (int _i = 0; _i < 2; ++_i) \
;         __builtin_amdgcn_global_load_lds((const unsigned*)((const char*)(gbase) + (voff)[_i]), (PG8_LAS unsigned*)(lds + (bufoff) + ldsw + _i * 8192), 16, 0, 0); } while (0)
; #define PG8_LDA(dst, b, h) do { _Pragma("unroll") for (int m = 0; m < 4; ++m) _Pragma("unroll") for (int k = 0; k < 2; ++k) dst[m][k] = *(const PG8_LAS bf16x8*)(lds + PG8_SA(b, h) + aoff + m * 2048 + k * 1024); } while (0)
; #define PG8_MMA(ai, bj, At, Bt) do { __builtin_amdgcn_s_setprio(1); _Pragma("unroll") for (int m = 0; m < 4; ++m) _Pragma("unroll") for (int n = 0; n < 2; ++n) _Pragma("unroll") for (int k = 0; k < 2; ++k) \
;         acc[ai][bj][m][n] = __builtin_amdgcn_mfma_f32_16x16x32_bf16(Bt[n][k], At[m][k], acc[ai][bj][m][n], 0, 0, 0); __builtin_amdgcn_s_setprio(0); } while (0)
; #define PG8_WAIT_V(n) asm volatile("s_waitcnt vmcnt(" #n ")" ::: "memory")
; #define PG8_WAIT_L(n) asm volatile("s_waitcnt lgkmcnt(" #n ")" ::: "memory")
; #define PG8_BAR __builtin_amdgcn_s_barrier()
; #define PG8_SCHED __builtin_amdgcn_sched_barrier(0)
; template <class Epi, class Sched, bool ALIGN_EPI = false, bool SP2 = false>
; __device__ __forceinline__ void gemm_phase(PG8_LAS unsigned char* lds, const Gemm g, const Sched& S, const Epi& E) {
;     ...
;             PG8_LDA(At, 1, 1); PG8_STAGE(PG8_SB(1, 0), b3, voffB); PG8_STAGE(PG8_SB(1, 1), b3 + hstepB, voffB); PG8_STAGE(PG8_SA(1, 0), a3, voffA);
;             PG8_WAIT_V(8); PG8_WAIT_L(0); PG8_BAR; PG8_MMA(1, 0, At, B0); PG8_MMA(1, 1, At, B1); PG8_BAR; PG8_SCHED;
	s_add_i32 s36, s64, s39
	v_lshl_add_u64 v[216:217], v[216:217], 0, s[6:7]
	s_mov_b32 m0, s36
	ds_read_b128 v[184:187], v170 offset:49152
	ds_read_b128 v[188:191], v170 offset:50176
	ds_read_b128 v[192:195], v170 offset:51200
	ds_read_b128 v[196:199], v170 offset:52224
	ds_read_b128 v[200:203], v170 offset:53248
	ds_read_b128 v[204:207], v170 offset:54272
	ds_read_b128 v[208:211], v170 offset:55296
	ds_read_b128 v[212:215], v170 offset:56320
	global_load_lds_dwordx4 v[216:217], off
	s_add_i32 m0, s36, 0x2000
	s_add_u32 s34, s34, 0x100080
	v_lshl_add_u64 v[216:217], v[218:219], 0, s[6:7]
	s_addc_u32 s35, s35, 0
	s_add_i32 s36, s65, s39
	global_load_lds_dwordx4 v[216:217], off
	v_lshl_add_u64 v[216:217], s[34:35], 0, v[148:149]
	s_mov_b32 m0, s36
	s_nop 0
	global_load_lds_dwordx4 v[216:217], off
	v_lshl_add_u64 v[216:217], s[34:35], 0, v[152:153]
	s_add_i32 m0, s36, 0x2000
	s_nop 0
	global_load_lds_dwordx4 v[216:217], off
	v_lshl_add_u64 v[216:217], v[220:221], 0, s[6:7]
	s_mov_b32 m0, s47
	s_nop 0
	global_load_lds_dwordx4 v[216:217], off
	v_lshl_add_u64 v[216:217], v[222:223], 0, s[6:7]
	s_mov_b32 m0, s48
	s_nop 0
	global_load_lds_dwordx4 v[216:217], off
	s_waitcnt vmcnt(8)
	s_waitcnt lgkmcnt(0)
	s_barrier
	s_setprio 1
	s_waitcnt lgkmcnt(0)
	v_mfma_f32_16x16x32_bf16 v[62:65], v[66:69], v[184:187], v[62:65]
	v_mfma_f32_16x16x32_bf16 v[46:49], v[66:69], v[192:195], v[46:49]
	v_mfma_f32_16x16x32_bf16 v[30:33], v[66:69], v[200:203], v[30:33]
	v_mfma_f32_16x16x32_bf16 v[22:25], v[66:69], v[208:211], v[22:25]
	v_mfma_f32_16x16x32_bf16 v[18:21], v[74:77], v[208:211], v[18:21]
	v_mfma_f32_16x16x32_bf16 v[26:29], v[74:77], v[200:203], v[26:29]
	v_mfma_f32_16x16x32_bf16 v[42:45], v[74:77], v[192:195], v[42:45]
	v_mfma_f32_16x16x32_bf16 v[58:61], v[74:77], v[184:187], v[58:61]
	v_mfma_f32_16x16x32_bf16 v[62:65], v[70:73], v[188:191], v[62:65]
	v_mfma_f32_16x16x32_bf16 v[46:49], v[70:73], v[196:199], v[46:49]
	v_mfma_f32_16x16x32_bf16 v[30:33], v[70:73], v[204:207], v[30:33]
	v_mfma_f32_16x16x32_bf16 v[22:25], v[70:73], v[212:215], v[22:25]
	v_mfma_f32_16x16x32_bf16 v[18:21], v[78:81], v[212:215], v[18:21]
	v_mfma_f32_16x16x32_bf16 v[26:29], v[78:81], v[204:207], v[26:29]
	v_mfma_f32_16x16x32_bf16 v[42:45], v[78:81], v[196:199], v[42:45]
	v_mfma_f32_16x16x32_bf16 v[58:61], v[78:81], v[188:191], v[58:61]
	s_setprio 0
	s_setprio 1
	v_mfma_f32_16x16x32_bf16 v[54:57], v[162:165], v[184:187], v[54:57]
	v_mfma_f32_16x16x32_bf16 v[38:41], v[162:165], v[192:195], v[38:41]
	v_mfma_f32_16x16x32_bf16 v[14:17], v[162:165], v[200:203], v[14:17]
	v_mfma_f32_16x16x32_bf16 v[6:9], v[162:165], v[208:211], v[6:9]
	v_mfma_f32_16x16x32_bf16 v[2:5], v[176:179], v[208:211], v[2:5]
	v_mfma_f32_16x16x32_bf16 v[10:13], v[176:179], v[200:203], v[10:13]
	v_mfma_f32_16x16x32_bf16 v[34:37], v[176:179], v[192:195], v[34:37]
	v_mfma_f32_16x16x32_bf16 v[50:53], v[176:179], v[184:187], v[50:53]
	v_mfma_f32_16x16x32_bf16 v[54:57], v[172:175], v[188:191], v[54:57]
	v_mfma_f32_16x16x32_bf16 v[38:41], v[172:175], v[196:199], v[38:41]
	v_mfma_f32_16x16x32_bf16 v[14:17], v[172:175], v[204:207], v[14:17]
	v_mfma_f32_16x16x32_bf16 v[6:9], v[172:175], v[212:215], v[6:9]
	v_mfma_f32_16x16x32_bf16 v[2:5], v[180:183], v[212:215], v[2:5]
	v_mfma_f32_16x16x32_bf16 v[10:13], v[180:183], v[204:207], v[10:13]
	v_mfma_f32_16x16x32_bf16 v[34:37], v[180:183], v[196:199], v[34:37]
	v_mfma_f32_16x16x32_bf16 v[50:53], v[180:183], v[188:191], v[50:53]
	s_setprio 0
	s_barrier
	s_add_i32 s63, s63, 2
	s_add_u32 s30, s30, 0x100
	s_addc_u32 s31, s31, 0
	s_add_u32 s61, s61, 0x100
	s_addc_u32 s62, s62, 0
	s_cmp_gt_u32 s63, 61
	s_cbranch_scc0 .LBB0_1759
	s_and_b64 vcc, exec, s[8:9]
	s_cbranch_vccz .LBB0_1762
	s_barrier

; #define PG8_STAGE(bufoff, gbase, voff) do { _Pragma("unroll") for (int _i = 0; _i < 2; ++_i) \
;         __builtin_amdgcn_global_load_lds((const unsigned*)((const char*)(gbase) + (voff)[_i]), (PG8_LAS unsigned*)(lds + (bufoff) + ldsw + _i * 8192), 16, 0, 0); } while (0)
; #define PG8_LDA(dst, b, h) do { _Pragma("unroll") for (int m = 0; m < 4; ++m) _Pragma("unroll") for (int k = 0; k < 2; ++k) dst[m][k] = *(const PG8_LAS bf16x8*)(lds + PG8_SA(b, h) + aoff + m * 2048 + k * 1024); } while (0)
; #define PG8_LDB(dst, b, h) do { _Pragma("unroll") for (int n = 0; n < 2; ++n) _Pragma("unroll") for (int k = 0; k < 2; ++k) dst[n][k] = *(const PG8_LAS bf16x8*)(lds + PG8_SB(b, h) + boff + n * 2048 + k * 1024); } while (0)
; #define PG8_MMA(ai, bj, At, Bt) do { __builtin_amdgcn_s_setprio(1); _Pragma("unroll") for (int m = 0; m < 4; ++m) _Pragma("unroll") for (int n = 0; n < 2; ++n) _Pragma("unroll") for (int k = 0; k < 2; ++k) \
;         acc[ai][bj][m][n] = __builtin_amdgcn_mfma_f32_16x16x32_bf16(Bt[n][k], At[m][k], acc[ai][bj][m][n], 0, 0, 0); __builtin_amdgcn_s_setprio(0); } while (0)
; #define PG8_WAIT_V(n) asm volatile("s_waitcnt vmcnt(" #n ")" ::: "memory")
; #define PG8_WAIT_L(n) asm volatile("s_waitcnt lgkmcnt(" #n ")" ::: "memory")
; #define PG8_BAR __builtin_amdgcn_s_barrier()
; #define PG8_SCHED __builtin_amdgcn_sched_barrier(0)
; template <class Epi, class Sched, bool ALIGN_EPI = false, bool SP2 = false>
; __device__ __forceinline__ void gemm_phase(PG8_LAS unsigned char* lds, const Gemm g, const Sched& S, const Epi& E) {
;     ...
;             PG8_LDB(B0, 0, 0); PG8_LDB(B1, 0, 1); PG8_SCHED; PG8_LDA(At, 0, 0); PG8_STAGE(PG8_SA(1, 1), a1 + hstep, voffA);
;             PG8_WAIT_V(8); PG8_WAIT_L(0); PG8_BAR; PG8_MMA(0, 0, At, B0); PG8_MMA(0, 1, At, B1); PG8_BAR; PG8_SCHED;
;             PG8_LDA(At, 0, 1); PG8_STAGE(PG8_SB(0, 0), b2, voffB); PG8_STAGE(PG8_SB(0, 1), b2 + hstepB, voffB); PG8_STAGE(PG8_SA(0, 0), a2, voffA);
;             PG8_WAIT_V(8); PG8_WAIT_L(0); PG8_BAR; PG8_MMA(1, 0, At, B0); PG8_MMA(1, 1, At, B1); PG8_BAR; PG8_SCHED;
.LBB0_1889:
	ds_read_b128 v[146:149], v152
	ds_read_b128 v[156:159], v152 offset:1024
	ds_read_b128 v[160:163], v152 offset:2048
	ds_read_b128 v[164:167], v152 offset:3072
	ds_read_b128 v[168:171], v153
	ds_read_b128 v[172:175], v153 offset:1024
	ds_read_b128 v[176:179], v153 offset:2048
	ds_read_b128 v[180:183], v153 offset:3072
	s_add_u32 s16, s14, 0x100
	s_addc_u32 s17, s15, 0
	s_cmp_eq_u32 s44, 60
	s_cselect_b32 s21, s5, s17
	s_cselect_b32 s20, s4, s16
	s_cselect_b32 s19, s13, s43
	s_cselect_b32 s18, s12, s42
	v_lshl_add_u64 v[216:217], s[14:15], 0, v[138:139]
	s_add_i32 m0, s26, 0xc000
	ds_read_b128 v[184:187], v154
	ds_read_b128 v[188:191], v154 offset:1024
	ds_read_b128 v[192:195], v154 offset:2048
	ds_read_b128 v[196:199], v154 offset:3072
	ds_read_b128 v[200:203], v154 offset:4096
	ds_read_b128 v[204:207], v154 offset:5120
	ds_read_b128 v[208:211], v154 offset:6144
	ds_read_b128 v[212:215], v154 offset:7168
	global_load_lds_dwordx4 v[216:217], off
	v_lshl_add_u64 v[216:217], s[14:15], 0, v[140:141]
	s_add_i32 m0, s26, 0xe000
	s_nop 0
	global_load_lds_dwordx4 v[216:217], off
	s_waitcnt vmcnt(8)
	s_waitcnt lgkmcnt(0)
	s_barrier
	s_setprio 1
	s_waitcnt lgkmcnt(0)
	v_mfma_f32_16x16x32_bf16 v[126:129], v[146:149], v[184:187], v[126:129]
	v_mfma_f32_16x16x32_bf16 v[110:113], v[146:149], v[192:195], v[110:113]
	v_mfma_f32_16x16x32_bf16 v[94:97], v[146:149], v[200:203], v[94:97]
	v_mfma_f32_16x16x32_bf16 v[78:81], v[146:149], v[208:211], v[78:81]
	v_mfma_f32_16x16x32_bf16 v[74:77], v[160:163], v[208:211], v[74:77]
	v_mfma_f32_16x16x32_bf16 v[90:93], v[160:163], v[200:203], v[90:93]
	v_mfma_f32_16x16x32_bf16 v[106:109], v[160:163], v[192:195], v[106:109]
	v_mfma_f32_16x16x32_bf16 v[122:125], v[160:163], v[184:187], v[122:125]
	v_mfma_f32_16x16x32_bf16 v[126:129], v[156:159], v[188:191], v[126:129]
	v_mfma_f32_16x16x32_bf16 v[110:113], v[156:159], v[196:199], v[110:113]
	v_mfma_f32_16x16x32_bf16 v[94:97], v[156:159], v[204:207], v[94:97]
	v_mfma_f32_16x16x32_bf16 v[78:81], v[156:159], v[212:215], v[78:81]
	v_mfma_f32_16x16x32_bf16 v[74:77], v[164:167], v[212:215], v[74:77]
	v_mfma_f32_16x16x32_bf16 v[90:93], v[164:167], v[204:207], v[90:93]
	v_mfma_f32_16x16x32_bf16 v[106:109], v[164:167], v[196:199], v[106:109]
	v_mfma_f32_16x16x32_bf16 v[122:125], v[164:167], v[188:191], v[122:125]
	s_setprio 0
	s_setprio 1
	v_mfma_f32_16x16x32_bf16 v[118:121], v[168:171], v[184:187], v[118:121]
	v_mfma_f32_16x16x32_bf16 v[102:105], v[168:171], v[192:195], v[102:105]
	v_mfma_f32_16x16x32_bf16 v[86:89], v[168:171], v[200:203], v[86:89]
	v_mfma_f32_16x16x32_bf16 v[70:73], v[168:171], v[208:211], v[70:73]
	v_mfma_f32_16x16x32_bf16 v[66:69], v[176:179], v[208:211], v[66:69]
	v_mfma_f32_16x16x32_bf16 v[82:85], v[176:179], v[200:203], v[82:85]
	v_mfma_f32_16x16x32_bf16 v[98:101], v[176:179], v[192:195], v[98:101]
	v_mfma_f32_16x16x32_bf16 v[114:117], v[176:179], v[184:187], v[114:117]
	v_mfma_f32_16x16x32_bf16 v[118:121], v[172:175], v[188:191], v[118:121]
	v_mfma_f32_16x16x32_bf16 v[102:105], v[172:175], v[196:199], v[102:105]
	v_mfma_f32_16x16x32_bf16 v[86:89], v[172:175], v[204:207], v[86:89]
	v_mfma_f32_16x16x32_bf16 v[70:73], v[172:175], v[212:215], v[70:73]
	v_mfma_f32_16x16x32_bf16 v[66:69], v[180:183], v[212:215], v[66:69]
	v_mfma_f32_16x16x32_bf16 v[82:85], v[180:183], v[204:207], v[82:85]
	v_mfma_f32_16x16x32_bf16 v[98:101], v[180:183], v[196:199], v[98:101]
	v_mfma_f32_16x16x32_bf16 v[114:117], v[180:183], v[188:191], v[114:117]
	s_setprio 0
	s_barrier
	s_add_i32 s14, s35, s2
	v_lshl_add_u64 v[216:217], s[18:19], 0, v[134:135]
	s_mov_b32 m0, s14
	ds_read_b128 v[184:187], v154 offset:16384
	ds_read_b128 v[188:191], v154 offset:17408
	ds_read_b128 v[192:195], v154 offset:18432
	ds_read_b128 v[196:199], v154 offset:19456
	ds_read_b128 v[200:203], v154 offset:20480
	ds_read_b128 v[204:207], v154 offset:21504
	ds_read_b128 v[208:211], v154 offset:22528
	ds_read_b128 v[212:215], v154 offset:23552
	global_load_lds_dwordx4 v[216:217], off
	s_add_i32 m0, s14, 0x2000
	s_add_u32 s14, s18, 0x108000
	v_lshl_add_u64 v[218:219], s[18:19], 0, v[130:131]
	s_addc_u32 s15, s19, 0
	s_add_i32 s45, s36, s2
	global_load_lds_dwordx4 v[218:219], off
	v_lshl_add_u64 v[220:221], s[14:15], 0, v[134:135]
	s_mov_b32 m0, s45
	v_lshl_add_u64 v[222:223], s[20:21], 0, v[132:133]
	global_load_lds_dwordx4 v[220:221], off
	v_lshl_add_u64 v[220:221], s[14:15], 0, v[130:131]
	s_add_i32 m0, s45, 0x2000
	s_nop 0
	global_load_lds_dwordx4 v[220:221], off
	v_lshl_add_u64 v[220:221], s[20:21], 0, v[136:137]
	s_mov_b32 m0, s26
	s_nop 0
	global_load_lds_dwordx4 v[220:221], off
	s_mov_b32 m0, s27
	s_nop 0
	global_load_lds_dwordx4 v[222:223], off
	s_waitcnt vmcnt(8)
	s_waitcnt lgkmcnt(0)
	s_barrier
; #define PG8_STAGE(bufoff, gbase, voff) do { _Pragma("unroll") for (int _i = 0; _i < 2; ++_i) \
;         __builtin_amdgcn_global_load_lds((const unsigned*)((const char*)(gbase) + (voff)[_i]), (PG8_LAS unsigned*)(lds + (bufoff) + ldsw + _i * 8192), 16, 0, 0); } while (0)
; #define PG8_LDA(dst, b, h) do { _Pragma("unroll") for (int m = 0; m < 4; ++m) _Pragma("unroll") for (int k = 0; k < 2; ++k) dst[m][k] = *(const PG8_LAS bf16x8*)(lds + PG8_SA(b, h) + aoff + m * 2048 + k * 1024); } while (0)
; #define PG8_LDB(dst, b, h) do { _Pragma("unroll") for (int n = 0; n < 2; ++n) _Pragma("unroll") for (int k = 0; k < 2; ++k) dst[n][k] = *(const PG8_LAS bf16x8*)(lds + PG8_SB(b, h) + boff + n * 2048 + k * 1024); } while (0)
; #define PG8_MMA(ai, bj, At, Bt) do { __builtin_amdgcn_s_setprio(1); _Pragma("unroll") for (int m = 0; m < 4; ++m) _Pragma("unroll") for (int n = 0; n < 2; ++n) _Pragma("unroll") for (int k = 0; k < 2; ++k) \
;         acc[ai][bj][m][n] = __builtin_amdgcn_mfma_f32_16x16x32_bf16(Bt[n][k], At[m][k], acc[ai][bj][m][n], 0, 0, 0); __builtin_amdgcn_s_setprio(0); } while (0)
; #define PG8_WAIT_V(n) asm volatile("s_waitcnt vmcnt(" #n ")" ::: "memory")
; #define PG8_WAIT_L(n) asm volatile("s_waitcnt lgkmcnt(" #n ")" ::: "memory")
; #define PG8_BAR __builtin_amdgcn_s_barrier()
; #define PG8_SCHED __builtin_amdgcn_sched_barrier(0)
; template <class Epi, class Sched, bool ALIGN_EPI = false, bool SP2 = false>
; __device__ __forceinline__ void gemm_phase(PG8_LAS unsigned char* lds, const Gemm g, const Sched& S, const Epi& E) {
;     ...
;             PG8_WAIT_V(8); PG8_WAIT_L(0); PG8_BAR; PG8_MMA(1, 0, At, B0); PG8_MMA(1, 1, At, B1); PG8_BAR; PG8_SCHED;
;             PG8_LDB(B0, 1, 0); PG8_LDB(B1, 1, 1); PG8_SCHED; PG8_LDA(At, 1, 0); PG8_STAGE(PG8_SA(0, 1), a2 + hstep, voffA);
;             PG8_WAIT_V(8); PG8_WAIT_L(0); PG8_BAR; PG8_MMA(0, 0, At, B0); PG8_MMA(0, 1, At, B1); PG8_BAR; PG8_SCHED;
	s_setprio 1
	s_waitcnt lgkmcnt(0)
	v_mfma_f32_16x16x32_bf16 v[62:65], v[146:149], v[184:187], v[62:65]
	v_mfma_f32_16x16x32_bf16 v[46:49], v[146:149], v[192:195], v[46:49]
	v_mfma_f32_16x16x32_bf16 v[30:33], v[146:149], v[200:203], v[30:33]
	v_mfma_f32_16x16x32_bf16 v[14:17], v[146:149], v[208:211], v[14:17]
	v_mfma_f32_16x16x32_bf16 v[10:13], v[160:163], v[208:211], v[10:13]
	v_mfma_f32_16x16x32_bf16 v[26:29], v[160:163], v[200:203], v[26:29]
	v_mfma_f32_16x16x32_bf16 v[42:45], v[160:163], v[192:195], v[42:45]
	v_mfma_f32_16x16x32_bf16 v[58:61], v[160:163], v[184:187], v[58:61]
	v_mfma_f32_16x16x32_bf16 v[62:65], v[156:159], v[188:191], v[62:65]
	v_mfma_f32_16x16x32_bf16 v[46:49], v[156:159], v[196:199], v[46:49]
	v_mfma_f32_16x16x32_bf16 v[30:33], v[156:159], v[204:207], v[30:33]
	v_mfma_f32_16x16x32_bf16 v[14:17], v[156:159], v[212:215], v[14:17]
	v_mfma_f32_16x16x32_bf16 v[10:13], v[164:167], v[212:215], v[10:13]
	v_mfma_f32_16x16x32_bf16 v[26:29], v[164:167], v[204:207], v[26:29]
	v_mfma_f32_16x16x32_bf16 v[42:45], v[164:167], v[196:199], v[42:45]
	v_mfma_f32_16x16x32_bf16 v[58:61], v[164:167], v[188:191], v[58:61]
	s_setprio 0
	s_setprio 1
	v_mfma_f32_16x16x32_bf16 v[54:57], v[168:171], v[184:187], v[54:57]
	v_mfma_f32_16x16x32_bf16 v[38:41], v[168:171], v[192:195], v[38:41]
	v_mfma_f32_16x16x32_bf16 v[22:25], v[168:171], v[200:203], v[22:25]
	v_mfma_f32_16x16x32_bf16 v[6:9], v[168:171], v[208:211], v[6:9]
	v_mfma_f32_16x16x32_bf16 v[2:5], v[176:179], v[208:211], v[2:5]
	v_mfma_f32_16x16x32_bf16 v[18:21], v[176:179], v[200:203], v[18:21]
	v_mfma_f32_16x16x32_bf16 v[34:37], v[176:179], v[192:195], v[34:37]
	v_mfma_f32_16x16x32_bf16 v[50:53], v[176:179], v[184:187], v[50:53]
	v_mfma_f32_16x16x32_bf16 v[54:57], v[172:175], v[188:191], v[54:57]
	v_mfma_f32_16x16x32_bf16 v[38:41], v[172:175], v[196:199], v[38:41]
	v_mfma_f32_16x16x32_bf16 v[22:25], v[172:175], v[204:207], v[22:25]
	v_mfma_f32_16x16x32_bf16 v[6:9], v[172:175], v[212:215], v[6:9]
	v_mfma_f32_16x16x32_bf16 v[2:5], v[180:183], v[212:215], v[2:5]
	v_mfma_f32_16x16x32_bf16 v[18:21], v[180:183], v[204:207], v[18:21]
	v_mfma_f32_16x16x32_bf16 v[34:37], v[180:183], v[196:199], v[34:37]
	v_mfma_f32_16x16x32_bf16 v[50:53], v[180:183], v[188:191], v[50:53]
	s_setprio 0
	s_barrier
	s_add_i32 s45, 0, 0x18000
	v_add_u32_e32 v155, s45, v150
	s_add_i32 s46, 0, 0x1c000
	ds_read_b128 v[146:149], v155
	ds_read_b128 v[156:159], v155 offset:1024
	ds_read_b128 v[160:163], v155 offset:2048
	ds_read_b128 v[164:167], v155 offset:3072
	v_add_u32_e32 v155, s46, v150
	ds_read_b128 v[168:171], v155
	ds_read_b128 v[172:175], v155 offset:1024
	ds_read_b128 v[176:179], v155 offset:2048
	ds_read_b128 v[180:183], v155 offset:3072
	s_add_u32 s14, s20, 0x108000
	s_addc_u32 s15, s21, 0
	s_mov_b32 m0, s28
	v_lshl_add_u64 v[224:225], s[14:15], 0, v[136:137]
	ds_read_b128 v[184:187], v154 offset:32768
	ds_read_b128 v[188:191], v154 offset:33792
	ds_read_b128 v[192:195], v154 offset:34816
	ds_read_b128 v[196:199], v154 offset:35840
	ds_read_b128 v[200:203], v154 offset:36864
	ds_read_b128 v[204:207], v154 offset:37888
	ds_read_b128 v[208:211], v154 offset:38912
	ds_read_b128 v[212:215], v154 offset:39936
	global_load_lds_dwordx4 v[224:225], off
	v_lshl_add_u64 v[224:225], s[14:15], 0, v[132:133]
	s_mov_b32 m0, s29
	s_nop 0
	global_load_lds_dwordx4 v[224:225], off
	s_waitcnt vmcnt(8)
	s_waitcnt lgkmcnt(0)
	s_barrier
	s_setprio 1
	s_waitcnt lgkmcnt(0)
	v_mfma_f32_16x16x32_bf16 v[126:129], v[146:149], v[184:187], v[126:129]
	v_mfma_f32_16x16x32_bf16 v[110:113], v[146:149], v[192:195], v[110:113]
	v_mfma_f32_16x16x32_bf16 v[94:97], v[146:149], v[200:203], v[94:97]
	v_mfma_f32_16x16x32_bf16 v[78:81], v[146:149], v[208:211], v[78:81]
	v_mfma_f32_16x16x32_bf16 v[74:77], v[160:163], v[208:211], v[74:77]
	v_mfma_f32_16x16x32_bf16 v[90:93], v[160:163], v[200:203], v[90:93]
	v_mfma_f32_16x16x32_bf16 v[106:109], v[160:163], v[192:195], v[106:109]
	v_mfma_f32_16x16x32_bf16 v[122:125], v[160:163], v[184:187], v[122:125]
	v_mfma_f32_16x16x32_bf16 v[126:129], v[156:159], v[188:191], v[126:129]
	v_mfma_f32_16x16x32_bf16 v[110:113], v[156:159], v[196:199], v[110:113]
	v_mfma_f32_16x16x32_bf16 v[94:97], v[156:159], v[204:207], v[94:97]
	v_mfma_f32_16x16x32_bf16 v[78:81], v[156:159], v[212:215], v[78:81]
	v_mfma_f32_16x16x32_bf16 v[74:77], v[164:167], v[212:215], v[74:77]
	v_mfma_f32_16x16x32_bf16 v[90:93], v[164:167], v[204:207], v[90:93]
	v_mfma_f32_16x16x32_bf16 v[106:109], v[164:167], v[196:199], v[106:109]
	v_mfma_f32_16x16x32_bf16 v[122:125], v[164:167], v[188:191], v[122:125]
	s_setprio 0
	s_setprio 1
	v_mfma_f32_16x16x32_bf16 v[118:121], v[168:171], v[184:187], v[118:121]
	v_mfma_f32_16x16x32_bf16 v[102:105], v[168:171], v[192:195], v[102:105]
	v_mfma_f32_16x16x32_bf16 v[86:89], v[168:171], v[200:203], v[86:89]
	v_mfma_f32_16x16x32_bf16 v[70:73], v[168:171], v[208:211], v[70:73]
	v_mfma_f32_16x16x32_bf16 v[66:69], v[176:179], v[208:211], v[66:69]
	v_mfma_f32_16x16x32_bf16 v[82:85], v[176:179], v[200:203], v[82:85]
	v_mfma_f32_16x16x32_bf16 v[98:101], v[176:179], v[192:195], v[98:101]
	v_mfma_f32_16x16x32_bf16 v[114:117], v[176:179], v[184:187], v[114:117]
	v_mfma_f32_16x16x32_bf16 v[118:121], v[172:175], v[188:191], v[118:121]
	v_mfma_f32_16x16x32_bf16 v[102:105], v[172:175], v[196:199], v[102:105]
	v_mfma_f32_16x16x32_bf16 v[86:89], v[172:175], v[204:207], v[86:89]
	v_mfma_f32_16x16x32_bf16 v[70:73], v[172:175], v[212:215], v[70:73]
	v_mfma_f32_16x16x32_bf16 v[66:69], v[180:183], v[212:215], v[66:69]
	v_mfma_f32_16x16x32_bf16 v[82:85], v[180:183], v[204:207], v[82:85]
	v_mfma_f32_16x16x32_bf16 v[98:101], v[180:183], v[196:199], v[98:101]
	v_mfma_f32_16x16x32_bf16 v[114:117], v[180:183], v[188:191], v[114:117]
	s_setprio 0
	s_barrier
; #define PG8_STAGE(bufoff, gbase, voff) do { _Pragma("unroll") for (int _i = 0; _i < 2; ++_i) \
;         __builtin_amdgcn_global_load_lds((const unsigned*)((const char*)(gbase) + (voff)[_i]), (PG8_LAS unsigned*)(lds + (bufoff) + ldsw + _i * 8192), 16, 0, 0); } while (0)
; #define PG8_LDA(dst, b, h) do { _Pragma("unroll") for (int m = 0; m < 4; ++m) _Pragma("unroll") for (int k = 0; k < 2; ++k) dst[m][k] = *(const PG8_LAS bf16x8*)(lds + PG8_SA(b, h) + aoff + m * 2048 + k * 1024); } while (0)
; #define PG8_MMA(ai, bj, At, Bt) do { __builtin_amdgcn_s_setprio(1); _Pragma("unroll") for (int m = 0; m < 4; ++m) _Pragma("unroll") for (int n = 0; n < 2; ++n) _Pragma("unroll") for (int k = 0; k < 2; ++k) \
;         acc[ai][bj][m][n] = __builtin_amdgcn_mfma_f32_16x16x32_bf16(Bt[n][k], At[m][k], acc[ai][bj][m][n], 0, 0, 0); __builtin_amdgcn_s_setprio(0); } while (0)
; #define PG8_WAIT_V(n) asm volatile("s_waitcnt vmcnt(" #n ")" ::: "memory")
; #define PG8_WAIT_L(n) asm volatile("s_waitcnt lgkmcnt(" #n ")" ::: "memory")
; #define PG8_BAR __builtin_amdgcn_s_barrier()
; #define PG8_SCHED __builtin_amdgcn_sched_barrier(0)
; template <class Epi, class Sched, bool ALIGN_EPI = false, bool SP2 = false>
; __device__ __forceinline__ void gemm_phase(PG8_LAS unsigned char* lds, const Gemm g, const Sched& S, const Epi& E) {
;     ...
;             PG8_LDA(At, 1, 1); PG8_STAGE(PG8_SB(1, 0), b3, voffB); PG8_STAGE(PG8_SB(1, 1), b3 + hstepB, voffB); PG8_STAGE(PG8_SA(1, 0), a3, voffA);
;             PG8_WAIT_V(8); PG8_WAIT_L(0); PG8_BAR; PG8_MMA(1, 0, At, B0); PG8_MMA(1, 1, At, B1); PG8_BAR; PG8_SCHED;
	s_add_i32 s14, s45, s2
	v_lshl_add_u64 v[216:217], v[216:217], 0, s[8:9]
	s_mov_b32 m0, s14
	ds_read_b128 v[184:187], v154 offset:49152
	ds_read_b128 v[188:191], v154 offset:50176
	ds_read_b128 v[192:195], v154 offset:51200
	ds_read_b128 v[196:199], v154 offset:52224
	ds_read_b128 v[200:203], v154 offset:53248
	ds_read_b128 v[204:207], v154 offset:54272
	ds_read_b128 v[208:211], v154 offset:55296
	ds_read_b128 v[212:215], v154 offset:56320
	global_load_lds_dwordx4 v[216:217], off
	s_add_i32 m0, s14, 0x2000
	s_add_u32 s14, s18, 0x108080
	v_lshl_add_u64 v[216:217], v[218:219], 0, s[8:9]
	s_addc_u32 s15, s19, 0
	s_add_i32 s18, s46, s2
	global_load_lds_dwordx4 v[216:217], off
	v_lshl_add_u64 v[216:217], s[14:15], 0, v[134:135]
	s_mov_b32 m0, s18
	s_nop 0
	global_load_lds_dwordx4 v[216:217], off
	v_lshl_add_u64 v[216:217], s[14:15], 0, v[130:131]
	s_add_i32 m0, s18, 0x2000
	s_nop 0
	global_load_lds_dwordx4 v[216:217], off
	v_lshl_add_u64 v[216:217], v[220:221], 0, s[8:9]
	s_mov_b32 m0, s31
	s_nop 0
	global_load_lds_dwordx4 v[216:217], off
	v_lshl_add_u64 v[216:217], v[222:223], 0, s[8:9]
	s_mov_b32 m0, s33
	s_nop 0
	global_load_lds_dwordx4 v[216:217], off
	s_waitcnt vmcnt(8)
	s_waitcnt lgkmcnt(0)
	s_barrier
	s_setprio 1
	s_waitcnt lgkmcnt(0)
	v_mfma_f32_16x16x32_bf16 v[62:65], v[146:149], v[184:187], v[62:65]
	v_mfma_f32_16x16x32_bf16 v[46:49], v[146:149], v[192:195], v[46:49]
	v_mfma_f32_16x16x32_bf16 v[30:33], v[146:149], v[200:203], v[30:33]
	v_mfma_f32_16x16x32_bf16 v[14:17], v[146:149], v[208:211], v[14:17]
	v_mfma_f32_16x16x32_bf16 v[10:13], v[160:163], v[208:211], v[10:13]
	v_mfma_f32_16x16x32_bf16 v[26:29], v[160:163], v[200:203], v[26:29]
	v_mfma_f32_16x16x32_bf16 v[42:45], v[160:163], v[192:195], v[42:45]
	v_mfma_f32_16x16x32_bf16 v[58:61], v[160:163], v[184:187], v[58:61]
	v_mfma_f32_16x16x32_bf16 v[62:65], v[156:159], v[188:191], v[62:65]
	v_mfma_f32_16x16x32_bf16 v[46:49], v[156:159], v[196:199], v[46:49]
	v_mfma_f32_16x16x32_bf16 v[30:33], v[156:159], v[204:207], v[30:33]
	v_mfma_f32_16x16x32_bf16 v[14:17], v[156:159], v[212:215], v[14:17]
	v_mfma_f32_16x16x32_bf16 v[10:13], v[164:167], v[212:215], v[10:13]
	v_mfma_f32_16x16x32_bf16 v[26:29], v[164:167], v[204:207], v[26:29]
	v_mfma_f32_16x16x32_bf16 v[42:45], v[164:167], v[196:199], v[42:45]
	v_mfma_f32_16x16x32_bf16 v[58:61], v[164:167], v[188:191], v[58:61]
	s_setprio 0
	s_setprio 1
	v_mfma_f32_16x16x32_bf16 v[54:57], v[168:171], v[184:187], v[54:57]
	v_mfma_f32_16x16x32_bf16 v[38:41], v[168:171], v[192:195], v[38:41]
	v_mfma_f32_16x16x32_bf16 v[22:25], v[168:171], v[200:203], v[22:25]
	v_mfma_f32_16x16x32_bf16 v[6:9], v[168:171], v[208:211], v[6:9]
	v_mfma_f32_16x16x32_bf16 v[2:5], v[176:179], v[208:211], v[2:5]
	v_mfma_f32_16x16x32_bf16 v[18:21], v[176:179], v[200:203], v[18:21]
	v_mfma_f32_16x16x32_bf16 v[34:37], v[176:179], v[192:195], v[34:37]
	v_mfma_f32_16x16x32_bf16 v[50:53], v[176:179], v[184:187], v[50:53]
	v_mfma_f32_16x16x32_bf16 v[54:57], v[172:175], v[188:191], v[54:57]
	v_mfma_f32_16x16x32_bf16 v[38:41], v[172:175], v[196:199], v[38:41]
	v_mfma_f32_16x16x32_bf16 v[22:25], v[172:175], v[204:207], v[22:25]
	v_mfma_f32_16x16x32_bf16 v[6:9], v[172:175], v[212:215], v[6:9]
	v_mfma_f32_16x16x32_bf16 v[2:5], v[180:183], v[212:215], v[2:5]
	v_mfma_f32_16x16x32_bf16 v[18:21], v[180:183], v[204:207], v[18:21]
	v_mfma_f32_16x16x32_bf16 v[34:37], v[180:183], v[196:199], v[34:37]
	v_mfma_f32_16x16x32_bf16 v[50:53], v[180:183], v[188:191], v[50:53]
	s_setprio 0
	s_barrier
	s_add_i32 s44, s44, 2
	s_add_u32 s42, s42, 0x100
	s_addc_u32 s43, s43, 0
	s_cmp_gt_u32 s44, 61
	s_mov_b64 s[14:15], s[16:17]
	s_cbranch_scc0 .LBB0_1889
	s_and_b64 vcc, exec, s[10:11]
	s_cbranch_vccz .LBB0_1892
	s_barrier

; #define PG8_STAGE(bufoff, gbase, voff) do { _Pragma("unroll") for (int _i = 0; _i < 2; ++_i) \
;         __builtin_amdgcn_global_load_lds((const unsigned*)((const char*)(gbase) + (voff)[_i]), (PG8_LAS unsigned*)(lds + (bufoff) + ldsw + _i * 8192), 16, 0, 0); } while (0)
; #define PG8_LDA(dst, b, h) do { _Pragma("unroll") for (int m = 0; m < 4; ++m) _Pragma("unroll") for (int k = 0; k < 2; ++k) dst[m][k] = *(const PG8_LAS bf16x8*)(lds + PG8_SA(b, h) + aoff + m * 2048 + k * 1024); } while (0)
; #define PG8_LDB(dst, b, h) do { _Pragma("unroll") for (int n = 0; n < 2; ++n) _Pragma("unroll") for (int k = 0; k < 2; ++k) dst[n][k] = *(const PG8_LAS bf16x8*)(lds + PG8_SB(b, h) + boff + n * 2048 + k * 1024); } while (0)
; #define PG8_MMA(ai, bj, At, Bt) do { __builtin_amdgcn_s_setprio(1); _Pragma("unroll") for (int m = 0; m < 4; ++m) _Pragma("unroll") for (int n = 0; n < 2; ++n) _Pragma("unroll") for (int k = 0; k < 2; ++k) \
;         acc[ai][bj][m][n] = __builtin_amdgcn_mfma_f32_16x16x32_bf16(Bt[n][k], At[m][k], acc[ai][bj][m][n], 0, 0, 0); __builtin_amdgcn_s_setprio(0); } while (0)
; #define PG8_WAIT_V(n) asm volatile("s_waitcnt vmcnt(" #n ")" ::: "memory")
; #define PG8_WAIT_L(n) asm volatile("s_waitcnt lgkmcnt(" #n ")" ::: "memory")
; #define PG8_BAR __builtin_amdgcn_s_barrier()
; #define PG8_SCHED __builtin_amdgcn_sched_barrier(0)
; template <class Epi, class Sched, bool ALIGN_EPI = false, bool SP2 = false>
; __device__ __forceinline__ void gemm_phase(PG8_LAS unsigned char* lds, const Gemm g, const Sched& S, const Epi& E) {
;     ...
;             PG8_LDB(B0, 0, 0); PG8_LDB(B1, 0, 1); PG8_SCHED; PG8_LDA(At, 0, 0); PG8_STAGE(PG8_SA(1, 1), a1 + hstep, voffA);
;             PG8_WAIT_V(8); PG8_WAIT_L(0); PG8_BAR; PG8_MMA(0, 0, At, B0); PG8_MMA(0, 1, At, B1); PG8_BAR; PG8_SCHED;
;             PG8_LDA(At, 0, 1); PG8_STAGE(PG8_SB(0, 0), b2, voffB); PG8_STAGE(PG8_SB(0, 1), b2 + hstepB, voffB); PG8_STAGE(PG8_SA(0, 0), a2, voffA);
;             PG8_WAIT_V(8); PG8_WAIT_L(0); PG8_BAR; PG8_MMA(1, 0, At, B0); PG8_MMA(1, 1, At, B1); PG8_BAR; PG8_SCHED;
.LBB0_2165:
	ds_read_b128 v[128:131], v167
	ds_read_b128 v[132:135], v167 offset:1024
	ds_read_b128 v[136:139], v167 offset:2048
	ds_read_b128 v[140:143], v167 offset:3072
	ds_read_b128 v[160:163], v168
	ds_read_b128 v[170:173], v168 offset:1024
	ds_read_b128 v[174:177], v168 offset:2048
	ds_read_b128 v[178:181], v168 offset:3072
	s_add_u32 s16, s14, 0x100
	s_addc_u32 s17, s15, 0
	s_cmpk_eq_i32 s57, 0xa8
	s_cselect_b32 s21, s5, s17
	s_cselect_b32 s20, s4, s16
	s_cselect_b32 s19, s13, s56
	s_cselect_b32 s18, s12, s55
	v_lshl_add_u64 v[214:215], s[14:15], 0, v[152:153]
	s_add_i32 m0, s25, 0xc000
	ds_read_b128 v[182:185], v169
	ds_read_b128 v[186:189], v169 offset:1024
	ds_read_b128 v[190:193], v169 offset:2048
	ds_read_b128 v[194:197], v169 offset:3072
	ds_read_b128 v[198:201], v169 offset:4096
	ds_read_b128 v[202:205], v169 offset:5120
	ds_read_b128 v[206:209], v169 offset:6144
	ds_read_b128 v[210:213], v169 offset:7168
	global_load_lds_dwordx4 v[214:215], off
	v_lshl_add_u64 v[214:215], s[14:15], 0, v[154:155]
	s_add_i32 m0, s25, 0xe000
	s_nop 0
	global_load_lds_dwordx4 v[214:215], off
	s_waitcnt vmcnt(8)
	s_waitcnt lgkmcnt(0)
	s_barrier
	s_setprio 1
	s_waitcnt lgkmcnt(0)
	v_mfma_f32_16x16x32_bf16 v[124:127], v[128:131], v[182:185], v[124:127]
	v_mfma_f32_16x16x32_bf16 v[116:119], v[128:131], v[190:193], v[116:119]
	v_mfma_f32_16x16x32_bf16 v[92:95], v[128:131], v[198:201], v[92:95]
	v_mfma_f32_16x16x32_bf16 v[80:83], v[128:131], v[206:209], v[80:83]
	v_mfma_f32_16x16x32_bf16 v[72:75], v[136:139], v[206:209], v[72:75]
	v_mfma_f32_16x16x32_bf16 v[88:91], v[136:139], v[198:201], v[88:91]
	v_mfma_f32_16x16x32_bf16 v[108:111], v[136:139], v[190:193], v[108:111]
	v_mfma_f32_16x16x32_bf16 v[120:123], v[136:139], v[182:185], v[120:123]
	v_mfma_f32_16x16x32_bf16 v[124:127], v[132:135], v[186:189], v[124:127]
	v_mfma_f32_16x16x32_bf16 v[116:119], v[132:135], v[194:197], v[116:119]
	v_mfma_f32_16x16x32_bf16 v[92:95], v[132:135], v[202:205], v[92:95]
	v_mfma_f32_16x16x32_bf16 v[80:83], v[132:135], v[210:213], v[80:83]
	v_mfma_f32_16x16x32_bf16 v[72:75], v[140:143], v[210:213], v[72:75]
	v_mfma_f32_16x16x32_bf16 v[88:91], v[140:143], v[202:205], v[88:91]
	v_mfma_f32_16x16x32_bf16 v[108:111], v[140:143], v[194:197], v[108:111]
	v_mfma_f32_16x16x32_bf16 v[120:123], v[140:143], v[186:189], v[120:123]
	s_setprio 0
	s_setprio 1
	v_mfma_f32_16x16x32_bf16 v[112:115], v[160:163], v[182:185], v[112:115]
	v_mfma_f32_16x16x32_bf16 v[100:103], v[160:163], v[190:193], v[100:103]
	v_mfma_f32_16x16x32_bf16 v[84:87], v[160:163], v[198:201], v[84:87]
	v_mfma_f32_16x16x32_bf16 v[68:71], v[160:163], v[206:209], v[68:71]
	v_mfma_f32_16x16x32_bf16 v[64:67], v[174:177], v[206:209], v[64:67]
	v_mfma_f32_16x16x32_bf16 v[76:79], v[174:177], v[198:201], v[76:79]
	v_mfma_f32_16x16x32_bf16 v[96:99], v[174:177], v[190:193], v[96:99]
	v_mfma_f32_16x16x32_bf16 v[104:107], v[174:177], v[182:185], v[104:107]
	v_mfma_f32_16x16x32_bf16 v[112:115], v[170:173], v[186:189], v[112:115]
	v_mfma_f32_16x16x32_bf16 v[100:103], v[170:173], v[194:197], v[100:103]
	v_mfma_f32_16x16x32_bf16 v[84:87], v[170:173], v[202:205], v[84:87]
	v_mfma_f32_16x16x32_bf16 v[68:71], v[170:173], v[210:213], v[68:71]
	v_mfma_f32_16x16x32_bf16 v[64:67], v[178:181], v[210:213], v[64:67]
	v_mfma_f32_16x16x32_bf16 v[76:79], v[178:181], v[202:205], v[76:79]
	v_mfma_f32_16x16x32_bf16 v[96:99], v[178:181], v[194:197], v[96:99]
	v_mfma_f32_16x16x32_bf16 v[104:107], v[178:181], v[186:189], v[104:107]
	s_setprio 0
	s_barrier
	s_add_i32 s14, s36, s24
	v_lshl_add_u64 v[214:215], s[18:19], 0, v[146:147]
	s_mov_b32 m0, s14
	ds_read_b128 v[182:185], v169 offset:16384
	ds_read_b128 v[186:189], v169 offset:17408
	ds_read_b128 v[190:193], v169 offset:18432
	ds_read_b128 v[194:197], v169 offset:19456
	ds_read_b128 v[198:201], v169 offset:20480
	ds_read_b128 v[202:205], v169 offset:21504
	ds_read_b128 v[206:209], v169 offset:22528
	ds_read_b128 v[210:213], v169 offset:23552
	global_load_lds_dwordx4 v[214:215], off
	s_add_i32 m0, s14, 0x2000
	s_add_u32 s14, s18, 0x2b0000
	v_lshl_add_u64 v[216:217], s[18:19], 0, v[150:151]
	s_addc_u32 s15, s19, 0
	s_add_i32 s58, s37, s24
	global_load_lds_dwordx4 v[216:217], off
	v_lshl_add_u64 v[218:219], s[14:15], 0, v[146:147]
	s_mov_b32 m0, s58
	v_lshl_add_u64 v[220:221], s[20:21], 0, v[148:149]
	global_load_lds_dwordx4 v[218:219], off
	v_lshl_add_u64 v[218:219], s[14:15], 0, v[150:151]
	s_add_i32 m0, s58, 0x2000
	s_nop 0
	global_load_lds_dwordx4 v[218:219], off
	v_lshl_add_u64 v[218:219], s[20:21], 0, v[144:145]
	s_mov_b32 m0, s25
	s_nop 0
	global_load_lds_dwordx4 v[218:219], off
	s_mov_b32 m0, s26
	s_nop 0
	global_load_lds_dwordx4 v[220:221], off
	s_waitcnt vmcnt(8)
	s_waitcnt lgkmcnt(0)
	s_barrier
; #define PG8_STAGE(bufoff, gbase, voff) do { _Pragma("unroll") for (int _i = 0; _i < 2; ++_i) \
;         __builtin_amdgcn_global_load_lds((const unsigned*)((const char*)(gbase) + (voff)[_i]), (PG8_LAS unsigned*)(lds + (bufoff) + ldsw + _i * 8192), 16, 0, 0); } while (0)
; #define PG8_LDA(dst, b, h) do { _Pragma("unroll") for (int m = 0; m < 4; ++m) _Pragma("unroll") for (int k = 0; k < 2; ++k) dst[m][k] = *(const PG8_LAS bf16x8*)(lds + PG8_SA(b, h) + aoff + m * 2048 + k * 1024); } while (0)
; #define PG8_LDB(dst, b, h) do { _Pragma("unroll") for (int n = 0; n < 2; ++n) _Pragma("unroll") for (int k = 0; k < 2; ++k) dst[n][k] = *(const PG8_LAS bf16x8*)(lds + PG8_SB(b, h) + boff + n * 2048 + k * 1024); } while (0)
; #define PG8_MMA(ai, bj, At, Bt) do { __builtin_amdgcn_s_setprio(1); _Pragma("unroll") for (int m = 0; m < 4; ++m) _Pragma("unroll") for (int n = 0; n < 2; ++n) _Pragma("unroll") for (int k = 0; k < 2; ++k) \
;         acc[ai][bj][m][n] = __builtin_amdgcn_mfma_f32_16x16x32_bf16(Bt[n][k], At[m][k], acc[ai][bj][m][n], 0, 0, 0); __builtin_amdgcn_s_setprio(0); } while (0)
; #define PG8_WAIT_V(n) asm volatile("s_waitcnt vmcnt(" #n ")" ::: "memory")
; #define PG8_WAIT_L(n) asm volatile("s_waitcnt lgkmcnt(" #n ")" ::: "memory")
; #define PG8_BAR __builtin_amdgcn_s_barrier()
; #define PG8_SCHED __builtin_amdgcn_sched_barrier(0)
; template <class Epi, class Sched, bool ALIGN_EPI = false, bool SP2 = false>
; __device__ __forceinline__ void gemm_phase(PG8_LAS unsigned char* lds, const Gemm g, const Sched& S, const Epi& E) {
;     ...
;             PG8_WAIT_V(8); PG8_WAIT_L(0); PG8_BAR; PG8_MMA(1, 0, At, B0); PG8_MMA(1, 1, At, B1); PG8_BAR; PG8_SCHED;
;             PG8_LDB(B0, 1, 0); PG8_LDB(B1, 1, 1); PG8_SCHED; PG8_LDA(At, 1, 0); PG8_STAGE(PG8_SA(0, 1), a2 + hstep, voffA);
;             PG8_WAIT_V(8); PG8_WAIT_L(0); PG8_BAR; PG8_MMA(0, 0, At, B0); PG8_MMA(0, 1, At, B1); PG8_BAR; PG8_SCHED;
	s_setprio 1
	s_waitcnt lgkmcnt(0)
	v_mfma_f32_16x16x32_bf16 v[60:63], v[128:131], v[182:185], v[60:63]
	v_mfma_f32_16x16x32_bf16 v[48:51], v[128:131], v[190:193], v[48:51]
	v_mfma_f32_16x16x32_bf16 v[28:31], v[128:131], v[198:201], v[28:31]
	v_mfma_f32_16x16x32_bf16 v[20:23], v[128:131], v[206:209], v[20:23]
	v_mfma_f32_16x16x32_bf16 v[12:15], v[136:139], v[206:209], v[12:15]
	v_mfma_f32_16x16x32_bf16 v[24:27], v[136:139], v[198:201], v[24:27]
	v_mfma_f32_16x16x32_bf16 v[40:43], v[136:139], v[190:193], v[40:43]
	v_mfma_f32_16x16x32_bf16 v[56:59], v[136:139], v[182:185], v[56:59]
	v_mfma_f32_16x16x32_bf16 v[60:63], v[132:135], v[186:189], v[60:63]
	v_mfma_f32_16x16x32_bf16 v[48:51], v[132:135], v[194:197], v[48:51]
	v_mfma_f32_16x16x32_bf16 v[28:31], v[132:135], v[202:205], v[28:31]
	v_mfma_f32_16x16x32_bf16 v[20:23], v[132:135], v[210:213], v[20:23]
	v_mfma_f32_16x16x32_bf16 v[12:15], v[140:143], v[210:213], v[12:15]
	v_mfma_f32_16x16x32_bf16 v[24:27], v[140:143], v[202:205], v[24:27]
	v_mfma_f32_16x16x32_bf16 v[40:43], v[140:143], v[194:197], v[40:43]
	v_mfma_f32_16x16x32_bf16 v[56:59], v[140:143], v[186:189], v[56:59]
	s_setprio 0
	s_setprio 1
	v_mfma_f32_16x16x32_bf16 v[52:55], v[160:163], v[182:185], v[52:55]
	v_mfma_f32_16x16x32_bf16 v[36:39], v[160:163], v[190:193], v[36:39]
	v_mfma_f32_16x16x32_bf16 v[16:19], v[160:163], v[198:201], v[16:19]
	v_mfma_f32_16x16x32_bf16 v[4:7], v[160:163], v[206:209], v[4:7]
	v_mfma_f32_16x16x32_bf16 v[0:3], v[174:177], v[206:209], v[0:3]
	v_mfma_f32_16x16x32_bf16 v[8:11], v[174:177], v[198:201], v[8:11]
	v_mfma_f32_16x16x32_bf16 v[32:35], v[174:177], v[190:193], v[32:35]
	v_mfma_f32_16x16x32_bf16 v[44:47], v[174:177], v[182:185], v[44:47]
	v_mfma_f32_16x16x32_bf16 v[52:55], v[170:173], v[186:189], v[52:55]
	v_mfma_f32_16x16x32_bf16 v[36:39], v[170:173], v[194:197], v[36:39]
	v_mfma_f32_16x16x32_bf16 v[16:19], v[170:173], v[202:205], v[16:19]
	v_mfma_f32_16x16x32_bf16 v[4:7], v[170:173], v[210:213], v[4:7]
	v_mfma_f32_16x16x32_bf16 v[0:3], v[178:181], v[210:213], v[0:3]
	v_mfma_f32_16x16x32_bf16 v[8:11], v[178:181], v[202:205], v[8:11]
	v_mfma_f32_16x16x32_bf16 v[32:35], v[178:181], v[194:197], v[32:35]
	v_mfma_f32_16x16x32_bf16 v[44:47], v[178:181], v[186:189], v[44:47]
	s_setprio 0
	s_barrier
	s_add_i32 s58, 0, 0x18000
	s_add_i32 s59, 0, 0x1c000
	v_add_u32_e32 v140, s58, v165
	v_add_u32_e32 v178, s59, v165
	ds_read_b128 v[128:131], v140
	ds_read_b128 v[132:135], v140 offset:1024
	ds_read_b128 v[136:139], v140 offset:2048
	ds_read_b128 v[140:143], v140 offset:3072
	ds_read_b128 v[160:163], v178
	ds_read_b128 v[170:173], v178 offset:1024
	ds_read_b128 v[174:177], v178 offset:2048
	ds_read_b128 v[178:181], v178 offset:3072
	s_add_u32 s14, s20, 0x2b0000
	s_addc_u32 s15, s21, 0
	s_mov_b32 m0, s27
	v_lshl_add_u64 v[222:223], s[14:15], 0, v[144:145]
	ds_read_b128 v[182:185], v169 offset:32768
	ds_read_b128 v[186:189], v169 offset:33792
	ds_read_b128 v[190:193], v169 offset:34816
	ds_read_b128 v[194:197], v169 offset:35840
	ds_read_b128 v[198:201], v169 offset:36864
	ds_read_b128 v[202:205], v169 offset:37888
	ds_read_b128 v[206:209], v169 offset:38912
	ds_read_b128 v[210:213], v169 offset:39936
	global_load_lds_dwordx4 v[222:223], off
	v_lshl_add_u64 v[222:223], s[14:15], 0, v[148:149]
	s_mov_b32 m0, s28
	s_nop 0
	global_load_lds_dwordx4 v[222:223], off
	s_waitcnt vmcnt(8)
	s_waitcnt lgkmcnt(0)
	s_barrier
	s_setprio 1
	s_waitcnt lgkmcnt(0)
	v_mfma_f32_16x16x32_bf16 v[124:127], v[128:131], v[182:185], v[124:127]
	v_mfma_f32_16x16x32_bf16 v[116:119], v[128:131], v[190:193], v[116:119]
	v_mfma_f32_16x16x32_bf16 v[92:95], v[128:131], v[198:201], v[92:95]
	v_mfma_f32_16x16x32_bf16 v[80:83], v[128:131], v[206:209], v[80:83]
	v_mfma_f32_16x16x32_bf16 v[72:75], v[136:139], v[206:209], v[72:75]
	v_mfma_f32_16x16x32_bf16 v[88:91], v[136:139], v[198:201], v[88:91]
	v_mfma_f32_16x16x32_bf16 v[108:111], v[136:139], v[190:193], v[108:111]
	v_mfma_f32_16x16x32_bf16 v[120:123], v[136:139], v[182:185], v[120:123]
	v_mfma_f32_16x16x32_bf16 v[124:127], v[132:135], v[186:189], v[124:127]
	v_mfma_f32_16x16x32_bf16 v[116:119], v[132:135], v[194:197], v[116:119]
	v_mfma_f32_16x16x32_bf16 v[92:95], v[132:135], v[202:205], v[92:95]
	v_mfma_f32_16x16x32_bf16 v[80:83], v[132:135], v[210:213], v[80:83]
	v_mfma_f32_16x16x32_bf16 v[72:75], v[140:143], v[210:213], v[72:75]
	v_mfma_f32_16x16x32_bf16 v[88:91], v[140:143], v[202:205], v[88:91]
	v_mfma_f32_16x16x32_bf16 v[108:111], v[140:143], v[194:197], v[108:111]
	v_mfma_f32_16x16x32_bf16 v[120:123], v[140:143], v[186:189], v[120:123]
	s_setprio 0
	s_setprio 1
	v_mfma_f32_16x16x32_bf16 v[112:115], v[160:163], v[182:185], v[112:115]
	v_mfma_f32_16x16x32_bf16 v[100:103], v[160:163], v[190:193], v[100:103]
	v_mfma_f32_16x16x32_bf16 v[84:87], v[160:163], v[198:201], v[84:87]
	v_mfma_f32_16x16x32_bf16 v[68:71], v[160:163], v[206:209], v[68:71]
	v_mfma_f32_16x16x32_bf16 v[64:67], v[174:177], v[206:209], v[64:67]
	v_mfma_f32_16x16x32_bf16 v[76:79], v[174:177], v[198:201], v[76:79]
	v_mfma_f32_16x16x32_bf16 v[96:99], v[174:177], v[190:193], v[96:99]
	v_mfma_f32_16x16x32_bf16 v[104:107], v[174:177], v[182:185], v[104:107]
	v_mfma_f32_16x16x32_bf16 v[112:115], v[170:173], v[186:189], v[112:115]
	v_mfma_f32_16x16x32_bf16 v[100:103], v[170:173], v[194:197], v[100:103]
	v_mfma_f32_16x16x32_bf16 v[84:87], v[170:173], v[202:205], v[84:87]
	v_mfma_f32_16x16x32_bf16 v[68:71], v[170:173], v[210:213], v[68:71]
	v_mfma_f32_16x16x32_bf16 v[64:67], v[178:181], v[210:213], v[64:67]
	v_mfma_f32_16x16x32_bf16 v[76:79], v[178:181], v[202:205], v[76:79]
	v_mfma_f32_16x16x32_bf16 v[96:99], v[178:181], v[194:197], v[96:99]
	v_mfma_f32_16x16x32_bf16 v[104:107], v[178:181], v[186:189], v[104:107]
	s_setprio 0
	s_barrier
; #define PG8_STAGE(bufoff, gbase, voff) do { _Pragma("unroll") for (int _i = 0; _i < 2; ++_i) \
;         __builtin_amdgcn_global_load_lds((const unsigned*)((const char*)(gbase) + (voff)[_i]), (PG8_LAS unsigned*)(lds + (bufoff) + ldsw + _i * 8192), 16, 0, 0); } while (0)
; #define PG8_LDA(dst, b, h) do { _Pragma("unroll") for (int m = 0; m < 4; ++m) _Pragma("unroll") for (int k = 0; k < 2; ++k) dst[m][k] = *(const PG8_LAS bf16x8*)(lds + PG8_SA(b, h) + aoff + m * 2048 + k * 1024); } while (0)
; #define PG8_MMA(ai, bj, At, Bt) do { __builtin_amdgcn_s_setprio(1); _Pragma("unroll") for (int m = 0; m < 4; ++m) _Pragma("unroll") for (int n = 0; n < 2; ++n) _Pragma("unroll") for (int k = 0; k < 2; ++k) \
;         acc[ai][bj][m][n] = __builtin_amdgcn_mfma_f32_16x16x32_bf16(Bt[n][k], At[m][k], acc[ai][bj][m][n], 0, 0, 0); __builtin_amdgcn_s_setprio(0); } while (0)
; #define PG8_WAIT_V(n) asm volatile("s_waitcnt vmcnt(" #n ")" ::: "memory")
; #define PG8_WAIT_L(n) asm volatile("s_waitcnt lgkmcnt(" #n ")" ::: "memory")
; #define PG8_BAR __builtin_amdgcn_s_barrier()
; #define PG8_SCHED __builtin_amdgcn_sched_barrier(0)
; template <class Epi, class Sched, bool ALIGN_EPI = false, bool SP2 = false>
; __device__ __forceinline__ void gemm_phase(PG8_LAS unsigned char* lds, const Gemm g, const Sched& S, const Epi& E) {
;     ...
;             PG8_LDA(At, 1, 1); PG8_STAGE(PG8_SB(1, 0), b3, voffB); PG8_STAGE(PG8_SB(1, 1), b3 + hstepB, voffB); PG8_STAGE(PG8_SA(1, 0), a3, voffA);
;             PG8_WAIT_V(8); PG8_WAIT_L(0); PG8_BAR; PG8_MMA(1, 0, At, B0); PG8_MMA(1, 1, At, B1); PG8_BAR; PG8_SCHED;
	s_add_i32 s14, s58, s24
	v_lshl_add_u64 v[214:215], v[214:215], 0, s[8:9]
	s_mov_b32 m0, s14
	ds_read_b128 v[182:185], v169 offset:49152
	ds_read_b128 v[186:189], v169 offset:50176
	ds_read_b128 v[190:193], v169 offset:51200
	ds_read_b128 v[194:197], v169 offset:52224
	ds_read_b128 v[198:201], v169 offset:53248
	ds_read_b128 v[202:205], v169 offset:54272
	ds_read_b128 v[206:209], v169 offset:55296
	ds_read_b128 v[210:213], v169 offset:56320
	global_load_lds_dwordx4 v[214:215], off
	s_add_i32 m0, s14, 0x2000
	s_add_u32 s14, s18, 0x2b0080
	v_lshl_add_u64 v[214:215], v[216:217], 0, s[8:9]
	s_addc_u32 s15, s19, 0
	s_add_i32 s18, s59, s24
	global_load_lds_dwordx4 v[214:215], off
	v_lshl_add_u64 v[214:215], s[14:15], 0, v[146:147]
	s_mov_b32 m0, s18
	s_nop 0
	global_load_lds_dwordx4 v[214:215], off
	v_lshl_add_u64 v[214:215], s[14:15], 0, v[150:151]
	s_add_i32 m0, s18, 0x2000
	s_nop 0
	global_load_lds_dwordx4 v[214:215], off
	v_lshl_add_u64 v[214:215], v[218:219], 0, s[8:9]
	s_mov_b32 m0, s33
	s_nop 0
	global_load_lds_dwordx4 v[214:215], off
	v_lshl_add_u64 v[214:215], v[220:221], 0, s[8:9]
	s_mov_b32 m0, s34
	s_nop 0
	global_load_lds_dwordx4 v[214:215], off
	s_waitcnt vmcnt(8)
	s_waitcnt lgkmcnt(0)
	s_barrier
	s_setprio 1
	s_waitcnt lgkmcnt(0)
	v_mfma_f32_16x16x32_bf16 v[60:63], v[128:131], v[182:185], v[60:63]
	v_mfma_f32_16x16x32_bf16 v[48:51], v[128:131], v[190:193], v[48:51]
	v_mfma_f32_16x16x32_bf16 v[28:31], v[128:131], v[198:201], v[28:31]
	v_mfma_f32_16x16x32_bf16 v[20:23], v[128:131], v[206:209], v[20:23]
	v_mfma_f32_16x16x32_bf16 v[12:15], v[136:139], v[206:209], v[12:15]
	v_mfma_f32_16x16x32_bf16 v[24:27], v[136:139], v[198:201], v[24:27]
	v_mfma_f32_16x16x32_bf16 v[40:43], v[136:139], v[190:193], v[40:43]
	v_mfma_f32_16x16x32_bf16 v[56:59], v[136:139], v[182:185], v[56:59]
	v_mfma_f32_16x16x32_bf16 v[60:63], v[132:135], v[186:189], v[60:63]
	v_mfma_f32_16x16x32_bf16 v[48:51], v[132:135], v[194:197], v[48:51]
	v_mfma_f32_16x16x32_bf16 v[28:31], v[132:135], v[202:205], v[28:31]
	v_mfma_f32_16x16x32_bf16 v[20:23], v[132:135], v[210:213], v[20:23]
	v_mfma_f32_16x16x32_bf16 v[12:15], v[140:143], v[210:213], v[12:15]
	v_mfma_f32_16x16x32_bf16 v[24:27], v[140:143], v[202:205], v[24:27]
	v_mfma_f32_16x16x32_bf16 v[40:43], v[140:143], v[194:197], v[40:43]
	v_mfma_f32_16x16x32_bf16 v[56:59], v[140:143], v[186:189], v[56:59]
	s_setprio 0
	s_setprio 1
	v_mfma_f32_16x16x32_bf16 v[52:55], v[160:163], v[182:185], v[52:55]
	v_mfma_f32_16x16x32_bf16 v[36:39], v[160:163], v[190:193], v[36:39]
	v_mfma_f32_16x16x32_bf16 v[16:19], v[160:163], v[198:201], v[16:19]
	v_mfma_f32_16x16x32_bf16 v[4:7], v[160:163], v[206:209], v[4:7]
	v_mfma_f32_16x16x32_bf16 v[0:3], v[174:177], v[206:209], v[0:3]
	v_mfma_f32_16x16x32_bf16 v[8:11], v[174:177], v[198:201], v[8:11]
	v_mfma_f32_16x16x32_bf16 v[32:35], v[174:177], v[190:193], v[32:35]
	v_mfma_f32_16x16x32_bf16 v[44:47], v[174:177], v[182:185], v[44:47]
	v_mfma_f32_16x16x32_bf16 v[52:55], v[170:173], v[186:189], v[52:55]
	v_mfma_f32_16x16x32_bf16 v[36:39], v[170:173], v[194:197], v[36:39]
	v_mfma_f32_16x16x32_bf16 v[16:19], v[170:173], v[202:205], v[16:19]
	v_mfma_f32_16x16x32_bf16 v[4:7], v[170:173], v[210:213], v[4:7]
	v_mfma_f32_16x16x32_bf16 v[0:3], v[178:181], v[210:213], v[0:3]
	v_mfma_f32_16x16x32_bf16 v[8:11], v[178:181], v[202:205], v[8:11]
	v_mfma_f32_16x16x32_bf16 v[32:35], v[178:181], v[194:197], v[32:35]
	v_mfma_f32_16x16x32_bf16 v[44:47], v[178:181], v[186:189], v[44:47]
	s_setprio 0
	s_barrier
	s_add_i32 s57, s57, 2
	s_add_u32 s55, s55, 0x100
	s_addc_u32 s56, s56, 0
	s_cmpk_gt_u32 s57, 0xa9
	s_mov_b64 s[14:15], s[16:17]
	s_cbranch_scc0 .LBB0_2165
	s_and_b64 vcc, exec, s[10:11]
	s_cbranch_vccz .LBB0_2168
	s_barrier
